# v46 + packed f32 ops (v_pk_mul/add/fma_f32) split into scalar pairs in the P1/P9 SwiGLU GEMM phases (strategy: instruction selection, bit-identical)
# speedup vs baseline: 1.0018x; 1.0018x over previous
.LBB0_127:
	s_add_u32 s54, s86, 0x5580000
	s_addc_u32 s55, s87, 0
	s_cmp_lt_i32 s60, 2
	s_cselect_b64 s[0:1], -1, 0
	s_cmp_gt_i32 s61, 1
	s_cselect_b64 s[4:5], -1, 0
	s_and_b64 s[0:1], s[0:1], s[4:5]
	v_writelane_b32 v253, s60, 34
	s_andn2_b64 vcc, exec, s[0:1]
	s_nop 0
	v_writelane_b32 v253, s61, 35
	s_cbranch_vccnz .LBB0_345
	s_abs_i32 s0, s3
	v_cvt_f32_u32_e32 v1, s0
	s_sub_i32 s1, 0, s0
	v_rcp_iflag_f32_e32 v1, v1
	s_nop 0
	v_mul_f32_e32 v1, 0x4f7ffffe, v1
	v_cvt_u32_f32_e32 v1, v1
	s_nop 0
	v_readfirstlane_b32 s4, v1
	s_mul_i32 s1, s1, s4
	s_mul_hi_u32 s1, s4, s1
	s_add_i32 s4, s4, s1
	s_mul_hi_u32 s1, s4, 0x580
	s_mul_i32 s1, s1, s0
	s_sub_i32 s1, 0x580, s1
	s_sub_i32 s4, s1, s0
	s_cmp_ge_u32 s1, s0
	s_cselect_b32 s1, s4, s1
	s_sub_i32 s4, s1, s0
	s_cmp_ge_u32 s1, s0
	s_cselect_b32 s12, s4, s1
	s_sub_i32 s14, s3, s12
	s_cmp_lg_u32 s12, 0
	s_cselect_b64 s[0:1], -1, 0
	s_cmp_gt_i32 s14, 43
	s_cselect_b64 s[4:5], -1, 0
	s_and_b64 s[0:1], s[0:1], s[4:5]
	s_andn2_b64 vcc, exec, s[0:1]
	s_mov_b64 s[0:1], -1
	s_cbranch_vccz .LBB0_135
	s_cmp_eq_u32 s12, 0
	s_cselect_b64 s[0:1], -1, 0
	s_cmpk_lt_i32 s14, 0x58
	s_cselect_b64 s[4:5], -1, 0
	s_or_b64 s[0:1], s[0:1], s[4:5]
	s_and_b64 s[0:1], s[0:1], exec
	s_cselect_b32 s0, 0, s12
	s_sub_i32 s0, s2, s0
	s_cmpk_gt_u32 s0, 0x57
	s_cbranch_scc1 .LBB0_134
	s_lshl_b32 s4, s0, 5
	s_lshl_b32 s0, s0, 6
	s_or_b32 s5, s4, 16
	s_and_b32 s0, s0, 0x1f00
	s_and_b32 s1, s4, 0x60
	v_and_b32_e32 v1, 15, v0
	s_or_b32 s6, s0, s1
	s_and_b32 s1, s5, 0x70
	v_lshlrev_b32_e32 v18, 11, v1
	v_mov_b32_e32 v19, 0
	s_or_b32 s7, s0, s1
	s_mov_b32 s1, 0
	v_lshl_add_u64 v[2:3], s[86:87], 0, v[18:19]
	s_lshl_b32 s0, s90, 8
	v_lshl_add_u64 v[2:3], v[2:3], 0, s[0:1]
	v_and_b32_e32 v18, 48, v0
	s_waitcnt lgkmcnt(0)
	v_lshl_add_u64 v[10:11], v[2:3], 0, v[18:19]
	s_mov_b32 s1, 0x10b000
	v_add_co_u32_e32 v2, vcc, s1, v10
	s_add_u32 s0, s34, s0
	s_nop 0
	v_addc_co_u32_e32 v3, vcc, 0, v11, vcc
	s_addc_u32 s1, s35, 0
	v_or_b32_e32 v6, s6, v1
	global_load_dwordx4 v[2:5], v[2:3], off
	v_lshl_add_u64 v[20:21], s[0:1], 0, v[18:19]
	v_lshlrev_b32_e32 v18, 11, v6
	v_lshl_add_u64 v[50:51], v[20:21], 0, v[18:19]
	s_mov_b32 s6, 0x40000
	v_or_b32_e32 v18, s7, v1
	v_add_co_u32_e32 v52, vcc, s6, v50
	v_lshlrev_b32_e32 v18, 11, v18
	s_nop 0
	v_addc_co_u32_e32 v53, vcc, 0, v51, vcc
	v_lshl_add_u64 v[54:55], v[20:21], 0, v[18:19]
	global_load_dwordx4 v[6:9], v[50:51], off
	global_load_dwordx4 v[14:17], v[52:53], off
	s_mov_b64 s[0:1], 0x10b000
	global_load_dwordx4 v[18:21], v[54:55], off
	v_add_co_u32_e32 v56, vcc, s6, v54
	v_lshl_add_u64 v[42:43], v[10:11], 0, s[0:1]
	s_nop 0
	v_addc_co_u32_e32 v57, vcc, 0, v55, vcc
	global_load_dwordx4 v[10:13], v[42:43], off offset:64
	global_load_dwordx4 v[22:25], v[56:57], off
	global_load_dwordx4 v[26:29], v[50:51], off offset:64
	global_load_dwordx4 v[30:33], v[42:43], off offset:192
	global_load_dwordx4 v[34:37], v[52:53], off offset:64
	global_load_dwordx4 v[38:41], v[54:55], off offset:64
	s_nop 0
	global_load_dwordx4 v[42:45], v[42:43], off offset:128
	s_lshl_b32 s0, s90, 12
	global_load_dwordx4 v[46:49], v[56:57], off offset:64
	s_add_i32 s0, s0, 0
	s_cmp_lt_u32 s92, 64
	s_waitcnt vmcnt(10)
	v_mfma_f32_16x16x32_bf16 v[6:9], v[2:5], v[6:9], 0
	s_waitcnt vmcnt(9)
	v_mfma_f32_16x16x32_bf16 v[14:17], v[2:5], v[14:17], 0
	s_waitcnt vmcnt(8)
	v_mfma_f32_16x16x32_bf16 v[18:21], v[2:5], v[18:21], 0
	s_waitcnt vmcnt(6)
	v_mfma_f32_16x16x32_bf16 v[2:5], v[2:5], v[22:25], 0
	global_load_dwordx4 v[22:25], v[50:51], off offset:128
	s_waitcnt vmcnt(6)
	v_mfma_f32_16x16x32_bf16 v[6:9], v[10:13], v[26:29], v[6:9]
	global_load_dwordx4 v[26:29], v[52:53], off offset:128
	s_waitcnt vmcnt(5)
	v_mfma_f32_16x16x32_bf16 v[14:17], v[10:13], v[34:37], v[14:17]
	global_load_dwordx4 v[34:37], v[54:55], off offset:128
	s_waitcnt vmcnt(5)
	v_mfma_f32_16x16x32_bf16 v[18:21], v[10:13], v[38:41], v[18:21]
	global_load_dwordx4 v[38:41], v[56:57], off offset:128
	s_waitcnt vmcnt(4)
	v_mfma_f32_16x16x32_bf16 v[2:5], v[10:13], v[46:49], v[2:5]
	global_load_dwordx4 v[10:13], v[50:51], off offset:192
	global_load_dwordx4 v[46:49], v[54:55], off offset:192
	s_waitcnt vmcnt(5)
	v_mfma_f32_16x16x32_bf16 v[6:9], v[42:45], v[22:25], v[6:9]
	global_load_dwordx4 v[22:25], v[52:53], off offset:192
	s_nop 0
	global_load_dwordx4 v[50:53], v[56:57], off offset:192
	s_waitcnt vmcnt(6)
	v_mfma_f32_16x16x32_bf16 v[26:29], v[42:45], v[26:29], v[14:17]
	s_waitcnt vmcnt(5)
	v_mfma_f32_16x16x32_bf16 v[34:37], v[42:45], v[34:37], v[18:21]
	s_waitcnt vmcnt(4)
	v_mfma_f32_16x16x32_bf16 v[2:5], v[42:45], v[38:41], v[2:5]
	s_waitcnt vmcnt(3)
	v_mfma_f32_16x16x32_bf16 v[14:17], v[30:33], v[10:13], v[6:9]
	s_nop 2
	v_lshlrev_b32_e32 v6, 4, v0
	v_and_b32_e32 v18, 0x3f0, v6
	s_waitcnt vmcnt(2)
	v_mfma_f32_16x16x32_bf16 v[10:13], v[30:33], v[46:49], v[34:37]
	v_add_u32_e32 v19, s0, v18
	s_cselect_b64 s[0:1], -1, 0
	s_cmp_gt_u32 s92, 63
	s_waitcnt vmcnt(1)
	v_mfma_f32_16x16x32_bf16 v[6:9], v[30:33], v[22:25], v[26:29]
	s_waitcnt vmcnt(0)
	v_mfma_f32_16x16x32_bf16 v[2:5], v[30:33], v[50:53], v[2:5]
	ds_write_b128 v19, v[14:17]
	s_nop 4
	ds_write_b128 v19, v[6:9] offset:1024
	ds_write_b128 v19, v[10:13] offset:2048
	ds_write_b128 v19, v[2:5] offset:3072
	s_waitcnt lgkmcnt(0)
	s_barrier
	s_cbranch_scc1 .LBB0_132
	v_add_u32_e32 v50, 0, v18
	ds_read_b128 v[18:21], v50 offset:4096
	ds_read_b128 v[22:25], v50 offset:8192
	ds_read_b128 v[26:29], v50 offset:12288
	ds_read_b128 v[30:33], v50 offset:5120
	s_waitcnt lgkmcnt(3)
	v_add_f32_e32 v16, v16, v20
	v_add_f32_e32 v17, v17, v21
	v_add_f32_e32 v14, v14, v18
	v_add_f32_e32 v15, v15, v19
	ds_read_b128 v[18:21], v50 offset:9216
	s_waitcnt lgkmcnt(3)
	v_add_f32_e32 v34, v16, v24
	v_add_f32_e32 v35, v17, v25
	v_add_f32_e32 v36, v14, v22
	v_add_f32_e32 v37, v15, v23
	ds_read_b128 v[14:17], v50 offset:16384
	ds_read_b128 v[22:25], v50 offset:13312
	s_waitcnt lgkmcnt(4)
	v_add_f32_e32 v38, v34, v28
	v_add_f32_e32 v39, v35, v29
	v_add_f32_e32 v40, v36, v26
	v_add_f32_e32 v41, v37, v27
	ds_read_b128 v[26:29], v50 offset:20480
	ds_read_b128 v[34:37], v50 offset:17408
	s_waitcnt lgkmcnt(3)
	v_add_f32_e32 v42, v38, v16
	v_add_f32_e32 v43, v39, v17
	v_add_f32_e32 v44, v40, v14
	v_add_f32_e32 v45, v41, v15
	ds_read_b128 v[14:17], v50 offset:24576
	ds_read_b128 v[38:41], v50 offset:21504
	s_waitcnt lgkmcnt(3)
	v_add_f32_e32 v46, v42, v28
	v_add_f32_e32 v47, v43, v29
	v_add_f32_e32 v48, v44, v26
	v_add_f32_e32 v49, v45, v27
	ds_read_b128 v[26:29], v50 offset:28672
	ds_read_b128 v[42:45], v50 offset:25600
	v_add_f32_e32 v8, v8, v32
	v_add_f32_e32 v9, v9, v33
	v_add_f32_e32 v6, v6, v30
	v_add_f32_e32 v7, v7, v31
	s_waitcnt lgkmcnt(3)
	v_add_f32_e32 v16, v46, v16
	v_add_f32_e32 v17, v47, v17
	v_add_f32_e32 v14, v48, v14
	v_add_f32_e32 v15, v49, v15
	ds_read_b128 v[46:49], v50 offset:29696
	v_add_f32_e32 v8, v8, v20
	v_add_f32_e32 v9, v9, v21
	v_add_f32_e32 v6, v6, v18
	v_add_f32_e32 v7, v7, v19
	ds_read_b128 v[18:21], v50 offset:6144
	s_waitcnt lgkmcnt(3)
	v_add_f32_e32 v16, v16, v28
	v_add_f32_e32 v17, v17, v29
	v_add_f32_e32 v14, v14, v26
	v_add_f32_e32 v15, v15, v27
	v_add_f32_e32 v8, v8, v24
	v_add_f32_e32 v9, v9, v25
	v_add_f32_e32 v6, v6, v22
	v_add_f32_e32 v7, v7, v23
	ds_read_b128 v[22:25], v50 offset:10240
	ds_read_b128 v[26:29], v50 offset:7168
	s_waitcnt lgkmcnt(2)
	v_add_f32_e32 v30, v12, v20
	v_add_f32_e32 v31, v13, v21
	v_add_f32_e32 v32, v10, v18
	v_add_f32_e32 v33, v11, v19
	ds_read_b128 v[10:13], v50 offset:14336
	ds_read_b128 v[18:21], v50 offset:11264
	v_add_f32_e32 v8, v8, v36
	v_add_f32_e32 v9, v9, v37
	v_add_f32_e32 v6, v6, v34
	v_add_f32_e32 v7, v7, v35
	s_waitcnt lgkmcnt(3)
	v_add_f32_e32 v34, v30, v24
	v_add_f32_e32 v35, v31, v25
	v_add_f32_e32 v36, v32, v22
	v_add_f32_e32 v37, v33, v23
	ds_read_b128 v[22:25], v50 offset:18432
	ds_read_b128 v[30:33], v50 offset:15360
	v_add_f32_e32 v8, v8, v40
	v_add_f32_e32 v9, v9, v41
	v_add_f32_e32 v6, v6, v38
	v_add_f32_e32 v7, v7, v39
	s_waitcnt lgkmcnt(3)
	v_add_f32_e32 v38, v34, v12
	v_add_f32_e32 v39, v35, v13
	v_add_f32_e32 v40, v36, v10
	v_add_f32_e32 v41, v37, v11
	ds_read_b128 v[10:13], v50 offset:22528
	ds_read_b128 v[34:37], v50 offset:19456
	v_add_f32_e32 v8, v8, v44
	v_add_f32_e32 v9, v9, v45
	v_add_f32_e32 v6, v6, v42
	v_add_f32_e32 v7, v7, v43
	s_waitcnt lgkmcnt(3)
	v_add_f32_e32 v42, v38, v24
	v_add_f32_e32 v43, v39, v25
	v_add_f32_e32 v44, v40, v22
	v_add_f32_e32 v45, v41, v23
	ds_read_b128 v[22:25], v50 offset:26624
	ds_read_b128 v[38:41], v50 offset:23552
	v_add_f32_e32 v8, v8, v48
	v_add_f32_e32 v9, v9, v49
	v_add_f32_e32 v6, v6, v46
	v_add_f32_e32 v7, v7, v47
	s_waitcnt lgkmcnt(3)
	v_add_f32_e32 v46, v42, v12
	v_add_f32_e32 v47, v43, v13
	v_add_f32_e32 v48, v44, v10
	v_add_f32_e32 v49, v45, v11
	ds_read_b128 v[10:13], v50 offset:30720
	ds_read_b128 v[42:45], v50 offset:27648
	v_add_f32_e32 v4, v4, v28
	v_add_f32_e32 v5, v5, v29
	v_add_f32_e32 v2, v2, v26
	v_add_f32_e32 v3, v3, v27
	s_waitcnt lgkmcnt(3)
	v_add_f32_e32 v46, v46, v24
	v_add_f32_e32 v47, v47, v25
	v_add_f32_e32 v48, v48, v22
	v_add_f32_e32 v49, v49, v23
	ds_read_b128 v[22:25], v50 offset:31744
	v_add_f32_e32 v4, v4, v20
	v_add_f32_e32 v5, v5, v21
	v_add_f32_e32 v2, v2, v18
	v_add_f32_e32 v3, v3, v19
	v_add_f32_e32 v4, v4, v32
	v_add_f32_e32 v5, v5, v33
	v_add_f32_e32 v2, v2, v30
	v_add_f32_e32 v3, v3, v31
	v_add_f32_e32 v4, v4, v36
	v_add_f32_e32 v5, v5, v37
	v_add_f32_e32 v2, v2, v34
	v_add_f32_e32 v3, v3, v35
	s_waitcnt lgkmcnt(3)
	v_add_f32_e32 v4, v4, v40
	v_add_f32_e32 v5, v5, v41
	v_add_f32_e32 v2, v2, v38
	v_add_f32_e32 v3, v3, v39
	s_waitcnt lgkmcnt(1)
	v_add_f32_e32 v4, v4, v44
	v_add_f32_e32 v5, v5, v45
	v_add_f32_e32 v2, v2, v42
	v_add_f32_e32 v3, v3, v43
	v_add_f32_e32 v12, v46, v12
	v_add_f32_e32 v13, v47, v13
	v_add_f32_e32 v10, v48, v10
	v_add_f32_e32 v11, v49, v11
	s_waitcnt lgkmcnt(0)
	v_add_f32_e32 v4, v4, v24
	v_add_f32_e32 v5, v5, v25
	v_add_f32_e32 v2, v2, v22
	v_add_f32_e32 v3, v3, v23

.LBB0_139:
	s_and_b32 s0, s15, 0x1f00
	s_and_b32 s1, s17, 0x60
	s_or_b32 s1, s0, s1
	v_or_b32_e32 v6, s1, v1
	global_load_dwordx4 v[2:5], v[20:21], off
	global_load_dwordx4 v[10:13], v[20:21], off offset:64
	v_lshlrev_b32_e32 v18, 11, v6
	s_add_i32 s1, s17, 16
	v_lshl_add_u64 v[68:69], v[22:23], 0, v[18:19]
	s_and_b32 s1, s1, 0x70
	s_or_b32 s0, s0, s1
	v_add_co_u32_e32 v70, vcc, s19, v68
	v_or_b32_e32 v18, s0, v1
	s_nop 0
	v_addc_co_u32_e32 v71, vcc, 0, v69, vcc
	global_load_dwordx4 v[6:9], v[68:69], off
	global_load_dwordx4 v[14:17], v[70:71], off
	v_lshlrev_b32_e32 v18, 11, v18
	v_lshl_add_u64 v[72:73], v[22:23], 0, v[18:19]
	v_add_co_u32_e32 v74, vcc, s19, v72
	global_load_dwordx4 v[36:39], v[72:73], off
	s_nop 0
	v_addc_co_u32_e32 v75, vcc, 0, v73, vcc
	global_load_dwordx4 v[40:43], v[74:75], off
	global_load_dwordx4 v[44:47], v[68:69], off offset:64
	global_load_dwordx4 v[48:51], v[70:71], off offset:64
	global_load_dwordx4 v[52:55], v[72:73], off offset:64
	global_load_dwordx4 v[56:59], v[20:21], off offset:128
	global_load_dwordx4 v[60:63], v[74:75], off offset:64
	s_and_b64 vcc, exec, s[4:5]
	s_waitcnt vmcnt(8)
	v_mfma_f32_16x16x32_bf16 v[6:9], v[2:5], v[6:9], 0
	s_waitcnt vmcnt(7)
	v_mfma_f32_16x16x32_bf16 v[14:17], v[2:5], v[14:17], 0
	s_waitcnt vmcnt(6)
	v_mfma_f32_16x16x32_bf16 v[36:39], v[2:5], v[36:39], 0
	s_waitcnt vmcnt(5)
	v_mfma_f32_16x16x32_bf16 v[2:5], v[2:5], v[40:43], 0
	global_load_dwordx4 v[40:43], v[68:69], off offset:128
	s_waitcnt vmcnt(5)
	v_mfma_f32_16x16x32_bf16 v[6:9], v[10:13], v[44:47], v[6:9]
	global_load_dwordx4 v[44:47], v[70:71], off offset:128
	s_waitcnt vmcnt(5)
	v_mfma_f32_16x16x32_bf16 v[14:17], v[10:13], v[48:51], v[14:17]
	global_load_dwordx4 v[48:51], v[72:73], off offset:128
	global_load_dwordx4 v[64:67], v[20:21], off offset:192
	s_waitcnt vmcnt(6)
	v_mfma_f32_16x16x32_bf16 v[36:39], v[10:13], v[52:55], v[36:39]
	global_load_dwordx4 v[52:55], v[74:75], off offset:128
	s_waitcnt vmcnt(5)
	v_mfma_f32_16x16x32_bf16 v[2:5], v[10:13], v[60:63], v[2:5]
	global_load_dwordx4 v[10:13], v[68:69], off offset:192
	global_load_dwordx4 v[60:63], v[72:73], off offset:192
	s_waitcnt vmcnt(6)
	v_mfma_f32_16x16x32_bf16 v[6:9], v[56:59], v[40:43], v[6:9]
	global_load_dwordx4 v[40:43], v[70:71], off offset:192
	s_waitcnt vmcnt(5)
	v_mfma_f32_16x16x32_bf16 v[36:39], v[56:59], v[48:51], v[36:39]
	global_load_dwordx4 v[48:51], v[74:75], off offset:192
	v_mfma_f32_16x16x32_bf16 v[44:47], v[56:59], v[44:47], v[14:17]
	s_waitcnt vmcnt(4)
	v_mfma_f32_16x16x32_bf16 v[2:5], v[56:59], v[52:55], v[2:5]
	s_waitcnt vmcnt(3)
	v_mfma_f32_16x16x32_bf16 v[14:17], v[64:67], v[10:13], v[6:9]
	s_waitcnt vmcnt(2)
	v_mfma_f32_16x16x32_bf16 v[10:13], v[64:67], v[60:63], v[36:39]
	s_waitcnt vmcnt(1)
	v_mfma_f32_16x16x32_bf16 v[6:9], v[64:67], v[40:43], v[44:47]
	s_waitcnt vmcnt(0)
	v_mfma_f32_16x16x32_bf16 v[2:5], v[64:67], v[48:51], v[2:5]
	s_nop 1
	ds_write_b128 v34, v[14:17]
	s_nop 2
	ds_write_b128 v34, v[6:9] offset:1024
	ds_write_b128 v34, v[10:13] offset:2048
	ds_write_b128 v34, v[2:5] offset:3072
	s_waitcnt lgkmcnt(0)
	s_barrier
	s_cbranch_vccnz .LBB0_141
	v_add_u32_e32 v18, 0, v32
	ds_read_b128 v[36:39], v18 offset:4096
	ds_read_b128 v[40:43], v18 offset:8192
	ds_read_b128 v[44:47], v18 offset:12288
	ds_read_b128 v[48:51], v18 offset:5120
	s_waitcnt lgkmcnt(3)
	v_add_f32_e32 v16, v16, v38
	v_add_f32_e32 v17, v17, v39
	v_add_f32_e32 v14, v14, v36
	v_add_f32_e32 v15, v15, v37
	ds_read_b128 v[36:39], v18 offset:9216
	s_waitcnt lgkmcnt(3)
	v_add_f32_e32 v52, v16, v42
	v_add_f32_e32 v53, v17, v43
	v_add_f32_e32 v54, v14, v40
	v_add_f32_e32 v55, v15, v41
	ds_read_b128 v[14:17], v18 offset:16384
	ds_read_b128 v[40:43], v18 offset:13312
	s_waitcnt lgkmcnt(4)
	v_add_f32_e32 v56, v52, v46
	v_add_f32_e32 v57, v53, v47
	v_add_f32_e32 v58, v54, v44
	v_add_f32_e32 v59, v55, v45
	ds_read_b128 v[44:47], v18 offset:20480
	ds_read_b128 v[52:55], v18 offset:17408
	s_waitcnt lgkmcnt(3)
	v_add_f32_e32 v60, v56, v16
	v_add_f32_e32 v61, v57, v17
	v_add_f32_e32 v62, v58, v14
	v_add_f32_e32 v63, v59, v15
	ds_read_b128 v[14:17], v18 offset:24576
	ds_read_b128 v[56:59], v18 offset:21504
	s_waitcnt lgkmcnt(3)
	v_add_f32_e32 v64, v60, v46
	v_add_f32_e32 v65, v61, v47
	v_add_f32_e32 v66, v62, v44
	v_add_f32_e32 v67, v63, v45
	ds_read_b128 v[44:47], v18 offset:28672
	ds_read_b128 v[60:63], v18 offset:25600
	v_add_f32_e32 v8, v8, v50
	v_add_f32_e32 v9, v9, v51
	v_add_f32_e32 v6, v6, v48
	v_add_f32_e32 v7, v7, v49
	s_waitcnt lgkmcnt(3)
	v_add_f32_e32 v16, v64, v16
	v_add_f32_e32 v17, v65, v17
	v_add_f32_e32 v14, v66, v14
	v_add_f32_e32 v15, v67, v15
	ds_read_b128 v[64:67], v18 offset:29696
	v_add_f32_e32 v8, v8, v38
	v_add_f32_e32 v9, v9, v39
	v_add_f32_e32 v6, v6, v36
	v_add_f32_e32 v7, v7, v37
	ds_read_b128 v[36:39], v18 offset:6144
	s_waitcnt lgkmcnt(3)
	v_add_f32_e32 v16, v16, v46
	v_add_f32_e32 v17, v17, v47
	v_add_f32_e32 v14, v14, v44
	v_add_f32_e32 v15, v15, v45
	v_add_f32_e32 v8, v8, v42
	v_add_f32_e32 v9, v9, v43
	v_add_f32_e32 v6, v6, v40
	v_add_f32_e32 v7, v7, v41
	ds_read_b128 v[40:43], v18 offset:10240
	ds_read_b128 v[44:47], v18 offset:7168
	s_waitcnt lgkmcnt(2)
	v_add_f32_e32 v48, v12, v38
	v_add_f32_e32 v49, v13, v39
	v_add_f32_e32 v50, v10, v36
	v_add_f32_e32 v51, v11, v37
	ds_read_b128 v[10:13], v18 offset:14336
	ds_read_b128 v[36:39], v18 offset:11264
	v_add_f32_e32 v8, v8, v54
	v_add_f32_e32 v9, v9, v55
	v_add_f32_e32 v6, v6, v52
	v_add_f32_e32 v7, v7, v53
	s_waitcnt lgkmcnt(3)
	v_add_f32_e32 v52, v48, v42
	v_add_f32_e32 v53, v49, v43
	v_add_f32_e32 v54, v50, v40
	v_add_f32_e32 v55, v51, v41
	ds_read_b128 v[40:43], v18 offset:18432
	ds_read_b128 v[48:51], v18 offset:15360
	v_add_f32_e32 v8, v8, v58
	v_add_f32_e32 v9, v9, v59
	v_add_f32_e32 v6, v6, v56
	v_add_f32_e32 v7, v7, v57
	s_waitcnt lgkmcnt(3)
	v_add_f32_e32 v56, v52, v12
	v_add_f32_e32 v57, v53, v13
	v_add_f32_e32 v58, v54, v10
	v_add_f32_e32 v59, v55, v11
	ds_read_b128 v[10:13], v18 offset:22528
	ds_read_b128 v[52:55], v18 offset:19456
	v_add_f32_e32 v8, v8, v62
	v_add_f32_e32 v9, v9, v63
	v_add_f32_e32 v6, v6, v60
	v_add_f32_e32 v7, v7, v61
	s_waitcnt lgkmcnt(3)
	v_add_f32_e32 v60, v56, v42
	v_add_f32_e32 v61, v57, v43
	v_add_f32_e32 v62, v58, v40
	v_add_f32_e32 v63, v59, v41
	ds_read_b128 v[40:43], v18 offset:26624
	ds_read_b128 v[56:59], v18 offset:23552
	v_add_f32_e32 v8, v8, v66
	v_add_f32_e32 v9, v9, v67
	v_add_f32_e32 v6, v6, v64
	v_add_f32_e32 v7, v7, v65
	s_waitcnt lgkmcnt(3)
	v_add_f32_e32 v64, v60, v12
	v_add_f32_e32 v65, v61, v13
	v_add_f32_e32 v66, v62, v10
	v_add_f32_e32 v67, v63, v11
	ds_read_b128 v[10:13], v18 offset:30720
	ds_read_b128 v[60:63], v18 offset:27648
	v_add_f32_e32 v4, v4, v46
	v_add_f32_e32 v5, v5, v47
	v_add_f32_e32 v2, v2, v44
	v_add_f32_e32 v3, v3, v45
	s_waitcnt lgkmcnt(3)
	v_add_f32_e32 v64, v64, v42
	v_add_f32_e32 v65, v65, v43
	v_add_f32_e32 v66, v66, v40
	v_add_f32_e32 v67, v67, v41
	ds_read_b128 v[40:43], v18 offset:31744
	v_add_f32_e32 v4, v4, v38
	v_add_f32_e32 v5, v5, v39
	v_add_f32_e32 v2, v2, v36
	v_add_f32_e32 v3, v3, v37
	v_add_f32_e32 v4, v4, v50
	v_add_f32_e32 v5, v5, v51
	v_add_f32_e32 v2, v2, v48
	v_add_f32_e32 v3, v3, v49
	v_add_f32_e32 v4, v4, v54
	v_add_f32_e32 v5, v5, v55
	v_add_f32_e32 v2, v2, v52
	v_add_f32_e32 v3, v3, v53
	s_waitcnt lgkmcnt(3)
	v_add_f32_e32 v4, v4, v58
	v_add_f32_e32 v5, v5, v59
	v_add_f32_e32 v2, v2, v56
	v_add_f32_e32 v3, v3, v57
	s_waitcnt lgkmcnt(1)
	v_add_f32_e32 v4, v4, v62
	v_add_f32_e32 v5, v5, v63
	v_add_f32_e32 v2, v2, v60
	v_add_f32_e32 v3, v3, v61
	v_add_f32_e32 v12, v64, v12
	v_add_f32_e32 v13, v65, v13
	v_add_f32_e32 v10, v66, v10
	v_add_f32_e32 v11, v67, v11
	s_waitcnt lgkmcnt(0)
	v_add_f32_e32 v4, v4, v42
	v_add_f32_e32 v5, v5, v43
	v_add_f32_e32 v2, v2, v40
	v_add_f32_e32 v3, v3, v41

.LBB0_148:
	s_cmpk_gt_i32 s16, 0x57f
	s_mov_b64 s[0:1], -1
	s_cbranch_scc0 .LBB0_214
	s_cmpk_gt_u32 s16, 0xaff
	s_cbranch_scc0 .LBB0_203
	s_cmpk_gt_u32 s16, 0x107f
	s_cbranch_scc0 .LBB0_200
	s_add_i32 s0, s16, 0xef80
	s_bfe_u32 s1, s0, 0xd0003
	s_mulk_i32 s1, 0xc31
	s_lshr_b32 s1, s1, 16
	s_mul_i32 s6, s1, 0xa8
	s_sub_i32 s18, s0, s6
	s_lshl_b32 s14, s1, 6
	v_or_b32_e32 v53, s14, v34
	s_lshl_b32 s0, s18, 7
	s_and_b32 s10, s0, 0x3ff80
	v_mul_u32_u24_e32 v4, 0x1500, v53
	v_lshl_add_u64 v[2:3], v[44:45], 0, s[10:11]
	v_lshlrev_b32_e32 v36, 2, v4
	v_lshl_add_u64 v[2:3], v[2:3], 0, v[36:37]
	s_mov_b32 s0, 0x2a000
	v_add_co_u32_e32 v4, vcc, s0, v2
	s_mov_b32 s0, 0x54000
	s_nop 0
	v_addc_co_u32_e32 v5, vcc, 0, v3, vcc
	global_load_dwordx4 v[26:29], v[2:3], off
	global_load_dwordx4 v[30:33], v[4:5], off
	v_add_co_u32_e32 v4, vcc, s0, v2
	s_mov_b32 s0, 0x7e000
	s_nop 0
	v_addc_co_u32_e32 v5, vcc, 0, v3, vcc
	v_add_co_u32_e32 v6, vcc, s0, v2
	v_mov_b32_e32 v52, 1.0
	s_nop 0
	v_addc_co_u32_e32 v7, vcc, 0, v3, vcc
	global_load_dwordx4 v[18:21], v[4:5], off
	global_load_dwordx4 v[22:25], v[6:7], off
	v_add_co_u32_e32 v4, vcc, s26, v2
	v_add_lshl_u32 v36, v34, s14, 2
	s_nop 0
	v_addc_co_u32_e32 v5, vcc, 0, v3, vcc
	v_add_co_u32_e32 v6, vcc, 0xd2000, v2
	v_mov_b32_e32 v59, 1.0
	s_nop 0
	v_addc_co_u32_e32 v7, vcc, 0, v3, vcc
	global_load_dwordx4 v[10:13], v[4:5], off
	global_load_dwordx4 v[14:17], v[6:7], off
	v_add_co_u32_e32 v4, vcc, 0xfc000, v2
	s_nop 1
	v_addc_co_u32_e32 v5, vcc, 0, v3, vcc
	v_add_co_u32_e32 v6, vcc, 0x126000, v2
	s_nop 1
	v_addc_co_u32_e32 v7, vcc, 0, v3, vcc
	global_load_dwordx4 v[2:5], v[4:5], off
	s_nop 0
	global_load_dwordx4 v[6:9], v[6:7], off
	s_and_b64 vcc, exec, s[4:5]
	s_cbranch_vccnz .LBB0_153
	v_lshlrev_b32_e32 v53, 2, v53
	global_load_dword v60, v53, s[80:81]
	global_load_dword v59, v36, s[80:81] offset:32
	s_waitcnt vmcnt(1)
	v_mul_f32_e32 v26, v26, v60
	v_mul_f32_e32 v27, v27, v60
	v_mul_f32_e32 v28, v28, v60
	v_mul_f32_e32 v29, v29, v60
.LBB0_153:
	s_waitcnt vmcnt(0)
	v_mul_f32_e32 v30, v30, v59
	ds_write2_b32 v1, v26, v30 offset1:8
	v_mul_f32_e32 v26, v31, v59
	ds_write2_b32 v1, v27, v26 offset0:66 offset1:74
	v_mul_f32_e32 v26, v32, v59
	ds_write2_b32 v1, v28, v26 offset0:132 offset1:140
	v_mul_f32_e32 v26, v33, v59
	s_and_b64 vcc, exec, s[4:5]
	ds_write2_b32 v1, v29, v26 offset0:198 offset1:206
	s_cbranch_vccnz .LBB0_155
	global_load_dword v26, v36, s[80:81] offset:64
	global_load_dword v52, v36, s[80:81] offset:96
	s_waitcnt vmcnt(1)
	v_mul_f32_e32 v18, v18, v26
	v_mul_f32_e32 v19, v19, v26
	v_mul_f32_e32 v20, v20, v26
	v_mul_f32_e32 v21, v21, v26
.LBB0_155:
	s_waitcnt vmcnt(0)
	v_mul_f32_e32 v22, v22, v52
	ds_write2_b32 v1, v18, v22 offset0:16 offset1:24
	v_mul_f32_e32 v18, v23, v52
	ds_write2_b32 v1, v19, v18 offset0:82 offset1:90
	v_mul_f32_e32 v18, v24, v52
	ds_write2_b32 v1, v20, v18 offset0:148 offset1:156
	v_mul_f32_e32 v18, v25, v52
	ds_write2_b32 v1, v21, v18 offset0:214 offset1:222
	v_mov_b32_e32 v18, 1.0
	s_and_b64 vcc, exec, s[4:5]
	v_mov_b32_e32 v19, 1.0
	s_cbranch_vccnz .LBB0_157
	global_load_dword v20, v36, s[80:81] offset:128
	global_load_dword v19, v36, s[80:81] offset:160
	s_waitcnt vmcnt(1)
	v_mul_f32_e32 v10, v10, v20
	v_mul_f32_e32 v11, v11, v20
	v_mul_f32_e32 v12, v12, v20
	v_mul_f32_e32 v13, v13, v20
.LBB0_157:
	s_waitcnt vmcnt(0)
	v_mul_f32_e32 v14, v14, v19
	ds_write2_b32 v1, v10, v14 offset0:32 offset1:40
	v_mul_f32_e32 v10, v15, v19
	ds_write2_b32 v1, v11, v10 offset0:98 offset1:106
	v_mul_f32_e32 v10, v16, v19
	ds_write2_b32 v1, v12, v10 offset0:164 offset1:172
	v_mul_f32_e32 v10, v17, v19
	s_and_b64 vcc, exec, s[4:5]
	ds_write2_b32 v1, v13, v10 offset0:230 offset1:238
	s_cbranch_vccnz .LBB0_159
	global_load_dword v10, v36, s[80:81] offset:192
	global_load_dword v18, v36, s[80:81] offset:224
	s_waitcnt vmcnt(1)
	v_mul_f32_e32 v2, v2, v10
	v_mul_f32_e32 v3, v3, v10
	v_mul_f32_e32 v4, v4, v10
	v_mul_f32_e32 v5, v5, v10

.LBB0_203:
	s_andn2_b64 vcc, exec, s[0:1]
	s_cbranch_vccnz .LBB0_213
	s_add_i32 s0, s16, 0xfa80
	s_and_b32 s1, s0, 0xffff
	s_mul_i32 s1, s1, 0xba2f
	s_lshr_b32 s6, s1, 16
	s_lshr_b32 s1, s1, 22
	s_mulk_i32 s1, 0x58
	s_sub_i32 s0, s0, s1
	s_and_b32 s1, s0, 0xffff
	s_and_b32 s0, s6, 0xffc0
	v_or_b32_e32 v53, s0, v34
	s_lshl_b32 s10, s1, 7
	v_lshl_add_u64 v[2:3], v[48:49], 0, s[10:11]
	v_mul_u32_u24_e32 v36, 0x2c00, v53
	v_mad_u64_u32 v[4:5], s[6:7], v53, s40, v[2:3]
	v_lshl_add_u64 v[2:3], v[2:3], 0, v[36:37]
	v_add_co_u32_e32 v6, vcc, s41, v2
	v_cndmask_b32_e64 v36, 0, 1, s[12:13]
	s_nop 0
	v_addc_co_u32_e32 v7, vcc, 0, v3, vcc
	global_load_dwordx4 v[26:29], v[4:5], off
	global_load_dwordx4 v[30:33], v[6:7], off
	v_add_co_u32_e32 v4, vcc, s42, v2
	v_mov_b32_e32 v52, 1.0
	s_nop 0
	v_addc_co_u32_e32 v5, vcc, 0, v3, vcc
	v_add_co_u32_e32 v6, vcc, s43, v2
	v_cmp_ne_u32_e64 s[6:7], 1, v36
	s_nop 0
	v_addc_co_u32_e32 v7, vcc, 0, v3, vcc
	global_load_dwordx4 v[18:21], v[4:5], off
	global_load_dwordx4 v[22:25], v[6:7], off
	v_add_co_u32_e32 v4, vcc, s44, v2
	v_add_lshl_u32 v36, v34, s0, 2
	s_nop 0
	v_addc_co_u32_e32 v5, vcc, 0, v3, vcc
	v_add_co_u32_e32 v6, vcc, 0x6e000, v2
	v_mov_b32_e32 v59, 1.0
	s_nop 0
	v_addc_co_u32_e32 v7, vcc, 0, v3, vcc
	global_load_dwordx4 v[10:13], v[4:5], off
	global_load_dwordx4 v[14:17], v[6:7], off
	v_add_co_u32_e32 v4, vcc, 0x84000, v2
	s_nop 1
	v_addc_co_u32_e32 v5, vcc, 0, v3, vcc
	v_add_co_u32_e32 v6, vcc, 0x9a000, v2
	s_nop 1
	v_addc_co_u32_e32 v7, vcc, 0, v3, vcc
	global_load_dwordx4 v[2:5], v[4:5], off
	s_nop 0
	global_load_dwordx4 v[6:9], v[6:7], off
	s_andn2_b64 vcc, exec, s[12:13]
	s_cbranch_vccnz .LBB0_206
	v_lshlrev_b32_e32 v53, 2, v53
	global_load_dword v60, v53, s[72:73]
	global_load_dword v59, v36, s[72:73] offset:32
	s_waitcnt vmcnt(1)
	v_mul_f32_e32 v26, v26, v60
	v_mul_f32_e32 v27, v27, v60
	v_mul_f32_e32 v28, v28, v60
	v_mul_f32_e32 v29, v29, v60
.LBB0_206:
	s_waitcnt vmcnt(0)
	v_mul_f32_e32 v30, v30, v59
	ds_write2_b32 v1, v26, v30 offset1:8
	v_mul_f32_e32 v26, v31, v59
	ds_write2_b32 v1, v27, v26 offset0:66 offset1:74
	v_mul_f32_e32 v26, v32, v59
	ds_write2_b32 v1, v28, v26 offset0:132 offset1:140
	v_mul_f32_e32 v26, v33, v59
	s_and_b64 vcc, exec, s[6:7]
	ds_write2_b32 v1, v29, v26 offset0:198 offset1:206
	s_cbranch_vccnz .LBB0_208
	global_load_dword v26, v36, s[72:73] offset:64
	global_load_dword v52, v36, s[72:73] offset:96
	s_waitcnt vmcnt(1)
	v_mul_f32_e32 v18, v18, v26
	v_mul_f32_e32 v19, v19, v26
	v_mul_f32_e32 v20, v20, v26
	v_mul_f32_e32 v21, v21, v26
.LBB0_208:
	s_waitcnt vmcnt(0)
	v_mul_f32_e32 v22, v22, v52
	ds_write2_b32 v1, v18, v22 offset0:16 offset1:24
	v_mul_f32_e32 v18, v23, v52
	ds_write2_b32 v1, v19, v18 offset0:82 offset1:90
	v_mul_f32_e32 v18, v24, v52
	ds_write2_b32 v1, v20, v18 offset0:148 offset1:156
	v_mul_f32_e32 v18, v25, v52
	ds_write2_b32 v1, v21, v18 offset0:214 offset1:222
	v_mov_b32_e32 v18, 1.0
	s_and_b64 vcc, exec, s[6:7]
	v_mov_b32_e32 v19, 1.0
	s_cbranch_vccnz .LBB0_210
	global_load_dword v20, v36, s[72:73] offset:128
	global_load_dword v19, v36, s[72:73] offset:160
	s_waitcnt vmcnt(1)
	v_mul_f32_e32 v10, v10, v20
	v_mul_f32_e32 v11, v11, v20
	v_mul_f32_e32 v12, v12, v20
	v_mul_f32_e32 v13, v13, v20
.LBB0_210:
	s_waitcnt vmcnt(0)
	v_mul_f32_e32 v14, v14, v19
	ds_write2_b32 v1, v10, v14 offset0:32 offset1:40
	v_mul_f32_e32 v10, v15, v19
	ds_write2_b32 v1, v11, v10 offset0:98 offset1:106
	v_mul_f32_e32 v10, v16, v19
	ds_write2_b32 v1, v12, v10 offset0:164 offset1:172
	v_mul_f32_e32 v10, v17, v19
	s_and_b64 vcc, exec, s[6:7]
	ds_write2_b32 v1, v13, v10 offset0:230 offset1:238
	s_cbranch_vccnz .LBB0_212
	global_load_dword v10, v36, s[72:73] offset:192
	global_load_dword v18, v36, s[72:73] offset:224
	s_waitcnt vmcnt(1)
	v_mul_f32_e32 v2, v2, v10
	v_mul_f32_e32 v3, v3, v10
	v_mul_f32_e32 v4, v4, v10
	v_mul_f32_e32 v5, v5, v10

.LBB0_214:
	s_andn2_b64 vcc, exec, s[0:1]
	s_cbranch_vccnz .LBB0_147
	s_mul_hi_i32 s0, s16, 0x2e8ba2e9
	s_lshr_b32 s1, s0, 31
	s_ashr_i32 s10, s0, 4
	s_add_i32 s10, s10, s1
	s_mul_i32 s0, s10, 0xfffff500
	s_lshl_b32 s6, s10, 6
	s_add_i32 s8, s20, s0
	v_or_b32_e32 v52, s6, v34
	s_ashr_i32 s9, s8, 31
	v_lshl_add_u64 v[2:3], s[8:9], 2, v[50:51]
	v_or_b32_e32 v6, 8, v52
	v_mad_i64_i32 v[4:5], s[0:1], v52, s40, v[2:3]
	v_mad_i64_i32 v[6:7], s[0:1], v6, s40, v[2:3]
	global_load_dwordx4 v[26:29], v[4:5], off
	global_load_dwordx4 v[30:33], v[6:7], off
	v_or_b32_e32 v4, 16, v52
	v_or_b32_e32 v6, 24, v52
	v_mad_i64_i32 v[4:5], s[0:1], v4, s40, v[2:3]
	v_mad_i64_i32 v[6:7], s[0:1], v6, s40, v[2:3]
	global_load_dwordx4 v[18:21], v[4:5], off
	global_load_dwordx4 v[22:25], v[6:7], off
	v_or_b32_e32 v4, 32, v52
	v_or_b32_e32 v6, 40, v52
	v_mad_i64_i32 v[4:5], s[0:1], v4, s40, v[2:3]
	v_mad_i64_i32 v[6:7], s[0:1], v6, s40, v[2:3]
	global_load_dwordx4 v[10:13], v[4:5], off
	global_load_dwordx4 v[14:17], v[6:7], off
	v_or_b32_e32 v4, 48, v52
	v_or_b32_e32 v6, 56, v52
	v_mad_i64_i32 v[4:5], s[0:1], v4, s40, v[2:3]
	v_mad_i64_i32 v[6:7], s[0:1], v6, s40, v[2:3]
	global_load_dwordx4 v[2:5], v[4:5], off
	s_nop 0
	global_load_dwordx4 v[6:9], v[6:7], off
	v_cndmask_b32_e64 v53, 0, 1, s[12:13]
	v_mov_b32_e32 v36, 1.0
	v_cmp_ne_u32_e64 s[0:1], 1, v53
	s_andn2_b64 vcc, exec, s[12:13]
	v_mov_b32_e32 v53, 1.0
	s_cbranch_vccnz .LBB0_217
	s_ashr_i32 s7, s6, 31
	v_ashrrev_i32_e32 v53, 31, v52
	v_lshl_add_u64 v[60:61], s[6:7], 0, v[34:35]
	v_lshl_add_u64 v[52:53], v[52:53], 2, s[72:73]
	v_lshl_add_u64 v[60:61], v[60:61], 2, s[72:73]
	global_load_dword v52, v[52:53], off
	s_nop 0
	global_load_dword v53, v[60:61], off offset:32
	s_waitcnt vmcnt(0)
	v_mul_f32_e32 v26, v26, v52
	v_mul_f32_e32 v27, v27, v52
	v_mul_f32_e32 v28, v28, v52
	v_mul_f32_e32 v29, v29, v52
.LBB0_217:
	s_waitcnt vmcnt(6)
	v_mul_f32_e32 v30, v30, v53
	ds_write2_b32 v1, v26, v30 offset1:8
	v_mul_f32_e32 v26, v31, v53
	ds_write2_b32 v1, v27, v26 offset0:66 offset1:74
	v_mul_f32_e32 v26, v32, v53
	ds_write2_b32 v1, v28, v26 offset0:132 offset1:140
	v_mul_f32_e32 v26, v33, v53
	s_and_b64 vcc, exec, s[0:1]
	ds_write2_b32 v1, v29, v26 offset0:198 offset1:206
	s_cbranch_vccnz .LBB0_219
	s_ashr_i32 s7, s6, 31
	v_lshl_add_u64 v[26:27], s[6:7], 0, v[34:35]
	v_lshl_add_u64 v[26:27], v[26:27], 2, s[72:73]
	global_load_dword v28, v[26:27], off offset:64
	global_load_dword v36, v[26:27], off offset:96
	s_waitcnt vmcnt(1)
	v_mul_f32_e32 v18, v18, v28
	v_mul_f32_e32 v19, v19, v28
	v_mul_f32_e32 v20, v20, v28
	v_mul_f32_e32 v21, v21, v28
.LBB0_219:
	s_waitcnt vmcnt(0)
	v_mul_f32_e32 v22, v22, v36
	ds_write2_b32 v1, v18, v22 offset0:16 offset1:24
	v_mul_f32_e32 v18, v23, v36
	ds_write2_b32 v1, v19, v18 offset0:82 offset1:90
	v_mul_f32_e32 v18, v24, v36
	ds_write2_b32 v1, v20, v18 offset0:148 offset1:156
	v_mul_f32_e32 v18, v25, v36
	s_and_b64 vcc, exec, s[0:1]
	ds_write2_b32 v1, v21, v18 offset0:214 offset1:222
	s_cbranch_vccnz .LBB0_221
	s_ashr_i32 s7, s6, 31
	v_lshl_add_u64 v[18:19], s[6:7], 0, v[34:35]
	v_lshl_add_u64 v[18:19], v[18:19], 2, s[72:73]
	global_load_dword v20, v[18:19], off offset:128
	s_nop 0
	global_load_dword v18, v[18:19], off offset:160
	s_waitcnt vmcnt(1)
	v_mul_f32_e32 v10, v10, v20
	v_mul_f32_e32 v11, v11, v20
	v_mul_f32_e32 v12, v12, v20
	v_mul_f32_e32 v13, v13, v20
	s_branch .LBB0_222

.LBB0_222:
	s_waitcnt vmcnt(0)
	v_mul_f32_e32 v14, v14, v18
	ds_write2_b32 v1, v10, v14 offset0:32 offset1:40
	v_mul_f32_e32 v10, v15, v18
	ds_write2_b32 v1, v11, v10 offset0:98 offset1:106
	v_mul_f32_e32 v10, v16, v18
	ds_write2_b32 v1, v12, v10 offset0:164 offset1:172
	v_mul_f32_e32 v10, v17, v18
	s_and_b64 vcc, exec, s[12:13]
	ds_write2_b32 v1, v13, v10 offset0:230 offset1:238
	s_cbranch_vccz .LBB0_224
	s_ashr_i32 s7, s6, 31
	v_lshl_add_u64 v[10:11], s[6:7], 0, v[34:35]
	v_lshl_add_u64 v[10:11], v[10:11], 2, s[72:73]
	global_load_dword v12, v[10:11], off offset:192
	s_nop 0
	global_load_dword v10, v[10:11], off offset:224
	s_waitcnt vmcnt(1)
	v_mul_f32_e32 v2, v2, v12
	v_mul_f32_e32 v3, v3, v12
	v_mul_f32_e32 v4, v4, v12
	v_mul_f32_e32 v5, v5, v12
	s_cbranch_execnz .LBB0_146
	s_branch .LBB0_225

.LBB0_285:
	v_lshl_add_u32 v131, s39, 10, v220
	ds_read2_b32 v[134:135], v131 offset1:16
	v_lshl_or_b32 v132, s93, 7, v219
	v_lshl_add_u32 v130, s38, 8, v1
	v_ashrrev_i32_e32 v133, 31, v132
	s_mov_b64 s[38:39], -1
	s_waitcnt lgkmcnt(0)
	v_mul_f32_e32 v122, v122, v134
	v_mul_f32_e32 v123, v123, v134
	v_mul_f32_e32 v126, v126, v134
	v_mul_f32_e32 v127, v127, v134
	v_mul_f32_e32 v136, 0xbfb8aa3b, v122
	v_mul_f32_e32 v137, 0xbfb8aa3b, v123
	v_exp_f32_e32 v136, v136
	v_exp_f32_e32 v137, v137
	v_mul_f32_e32 v124, v124, v134
	v_mul_f32_e32 v125, v125, v134
	v_mul_f32_e32 v114, v114, v134
	v_mul_f32_e32 v115, v115, v134
	v_add_f32_e32 v136, 1.0, v136
	v_add_f32_e32 v137, 1.0, v137
	v_rcp_f32_e32 v136, v136
	v_rcp_f32_e32 v137, v137
	v_mul_f32_e32 v118, v118, v134
	v_mul_f32_e32 v119, v119, v134
	v_mul_f32_e32 v116, v116, v134
	v_mul_f32_e32 v117, v117, v134
	v_mul_f32_e32 v120, v120, v134
	v_mul_f32_e32 v121, v121, v134
	v_mul_f32_e32 v122, v122, v136
	v_mul_f32_e32 v123, v123, v137
	v_mul_f32_e32 v128, v128, v134
	v_mul_f32_e32 v129, v129, v134
	v_mul_f32_e32 v122, v126, v122
	v_mul_f32_e32 v123, v127, v123
	v_mul_f32_e32 v126, 0xbfb8aa3b, v124
	v_mul_f32_e32 v127, 0xbfb8aa3b, v125
	v_exp_f32_e32 v126, v126
	v_exp_f32_e32 v127, v127
	s_andn2_b64 vcc, exec, s[4:5]
	v_add_f32_e32 v126, 1.0, v126
	v_add_f32_e32 v127, 1.0, v127
	v_rcp_f32_e32 v126, v126
	v_rcp_f32_e32 v127, v127
	s_nop 0
	v_mul_f32_e32 v124, v124, v126
	v_mul_f32_e32 v125, v125, v127
	v_mul_f32_e32 v126, 0xbfb8aa3b, v114
	v_mul_f32_e32 v127, 0xbfb8aa3b, v115
	v_exp_f32_e32 v126, v126
	v_exp_f32_e32 v127, v127
	v_mul_f32_e32 v124, v128, v124
	v_mul_f32_e32 v125, v129, v125
	v_add_f32_e32 v126, 1.0, v126
	v_add_f32_e32 v127, 1.0, v127
	v_rcp_f32_e32 v126, v126
	v_rcp_f32_e32 v127, v127
	s_nop 0
	v_mul_f32_e32 v114, v114, v126
	v_mul_f32_e32 v115, v115, v127
	s_nop 0
	v_mul_f32_e32 v114, v118, v114
	v_mul_f32_e32 v115, v119, v115
	v_mul_f32_e32 v118, 0xbfb8aa3b, v116
	v_mul_f32_e32 v119, 0xbfb8aa3b, v117
	v_exp_f32_e32 v118, v118
	v_exp_f32_e32 v119, v119
	v_add_f32_e32 v118, 1.0, v118
	v_add_f32_e32 v119, 1.0, v119
	v_rcp_f32_e32 v118, v118
	v_rcp_f32_e32 v119, v119
	s_nop 0
	v_mul_f32_e32 v116, v116, v118
	v_mul_f32_e32 v117, v117, v119
	s_nop 0
	v_mul_f32_e32 v116, v120, v116
	v_mul_f32_e32 v117, v121, v117
	v_cvt_pk_bf16_f32 v120, v114, v115
	v_mov_b64_e32 v[114:115], s[54:55]
	v_cvt_pk_bf16_f32 v118, v122, v123
	v_cvt_pk_bf16_f32 v121, v116, v117
	v_mad_i64_i32 v[122:123], s[18:19], v130, s67, v[114:115]
	v_lshlrev_b64 v[116:117], 1, v[132:133]
	v_cvt_pk_bf16_f32 v119, v124, v125
	v_lshl_add_u64 v[122:123], v[122:123], 0, v[116:117]
	global_store_dwordx4 v[122:123], v[118:121], off sc0 sc1
	s_nop 1
	v_mov_b32_e32 v118, v135
	v_mul_f32_e32 v106, v106, v118
	v_mul_f32_e32 v107, v107, v118
	s_nop 0
	v_mul_f32_e32 v119, 0xbfb8aa3b, v106
	v_exp_f32_e32 v119, v119
	s_nop 0
	v_add_f32_e32 v119, 1.0, v119
	v_rcp_f32_e32 v120, v119
	v_mul_f32_e32 v110, v110, v118
	v_mul_f32_e32 v111, v111, v118
	v_mul_f32_e32 v119, 0xbfb8aa3b, v107
	v_exp_f32_e32 v119, v119
	s_nop 0
	v_add_f32_e32 v119, 1.0, v119
	v_rcp_f32_e32 v121, v119
	v_mul_f32_e32 v108, v108, v118
	v_mul_f32_e32 v109, v109, v118
	v_mul_f32_e32 v98, v98, v118
	v_mul_f32_e32 v99, v99, v118
	v_mul_f32_e32 v102, v102, v118
	v_mul_f32_e32 v103, v103, v118
	v_mul_f32_e32 v106, v106, v120
	v_mul_f32_e32 v107, v107, v121
	v_mul_f32_e32 v112, v112, v118
	v_mul_f32_e32 v113, v113, v118
	v_mul_f32_e32 v106, v110, v106
	v_mul_f32_e32 v107, v111, v107
	v_mul_f32_e32 v110, 0xbfb8aa3b, v108
	v_mul_f32_e32 v111, 0xbfb8aa3b, v109
	v_exp_f32_e32 v110, v110
	v_exp_f32_e32 v111, v111
	v_mul_f32_e32 v104, v104, v118
	v_mul_f32_e32 v105, v105, v118
	v_add_f32_e32 v110, 1.0, v110
	v_add_f32_e32 v111, 1.0, v111
	v_rcp_f32_e32 v110, v110
	v_rcp_f32_e32 v111, v111
	s_nop 0
	v_mul_f32_e32 v108, v108, v110
	v_mul_f32_e32 v109, v109, v111
	v_mul_f32_e32 v110, 0xbfb8aa3b, v98
	v_mul_f32_e32 v111, 0xbfb8aa3b, v99
	v_exp_f32_e32 v110, v110
	v_exp_f32_e32 v111, v111
	v_mul_f32_e32 v108, v112, v108
	v_mul_f32_e32 v109, v113, v109
	v_add_f32_e32 v110, 1.0, v110
	v_add_f32_e32 v111, 1.0, v111
	v_rcp_f32_e32 v110, v110
	v_rcp_f32_e32 v111, v111
	s_nop 0
	v_mul_f32_e32 v98, v98, v110
	v_mul_f32_e32 v99, v99, v111
	s_nop 0
	v_mul_f32_e32 v102, v102, v98
	v_mul_f32_e32 v103, v103, v99
	v_mul_f32_e32 v98, v100, v118
	v_mul_f32_e32 v99, v101, v118
	v_or_b32_e32 v110, 16, v130
	v_mul_f32_e32 v100, 0xbfb8aa3b, v98
	v_mul_f32_e32 v101, 0xbfb8aa3b, v99
	v_exp_f32_e32 v100, v100
	v_exp_f32_e32 v101, v101
	v_add_f32_e32 v100, 1.0, v100
	v_add_f32_e32 v101, 1.0, v101
	v_rcp_f32_e32 v100, v100
	v_rcp_f32_e32 v101, v101
	s_nop 0
	v_mul_f32_e32 v98, v98, v100
	v_mul_f32_e32 v99, v99, v101
	s_nop 0
	v_mul_f32_e32 v104, v104, v98
	v_mul_f32_e32 v105, v105, v99
	v_cvt_pk_bf16_f32 v100, v102, v103
	v_mad_i64_i32 v[102:103], s[18:19], v110, s67, v[114:115]
	v_cvt_pk_bf16_f32 v98, v106, v107
	v_cvt_pk_bf16_f32 v99, v108, v109
	v_cvt_pk_bf16_f32 v101, v104, v105
	v_lshl_add_u64 v[102:103], v[102:103], 0, v[116:117]
	global_store_dwordx4 v[102:103], v[98:101], off sc0 sc1
	ds_read2_b32 v[98:99], v131 offset0:32 offset1:48
	s_waitcnt lgkmcnt(0)
	v_mul_f32_e32 v90, v90, v98
	v_mul_f32_e32 v91, v91, v98
	s_nop 0
	v_mul_f32_e32 v100, 0xbfb8aa3b, v90
	v_mul_f32_e32 v101, 0xbfb8aa3b, v91
	v_exp_f32_e32 v100, v100
	v_exp_f32_e32 v101, v101
	v_mul_f32_e32 v94, v94, v98
	v_mul_f32_e32 v95, v95, v98
	v_mul_f32_e32 v92, v92, v98
	v_mul_f32_e32 v93, v93, v98
	v_add_f32_e32 v100, 1.0, v100
	v_add_f32_e32 v101, 1.0, v101
	v_rcp_f32_e32 v100, v100
	v_rcp_f32_e32 v101, v101
	v_mul_f32_e32 v82, v82, v98
	v_mul_f32_e32 v83, v83, v98
	v_mul_f32_e32 v86, v86, v98
	v_mul_f32_e32 v87, v87, v98
	v_mul_f32_e32 v96, v96, v98
	v_mul_f32_e32 v97, v97, v98
	v_mul_f32_e32 v90, v90, v100
	v_mul_f32_e32 v91, v91, v101
	v_mul_f32_e32 v88, v88, v98
	v_mul_f32_e32 v89, v89, v98
	v_mul_f32_e32 v90, v94, v90
	v_mul_f32_e32 v91, v95, v91
	v_mul_f32_e32 v94, 0xbfb8aa3b, v92
	v_mul_f32_e32 v95, 0xbfb8aa3b, v93
	v_exp_f32_e32 v94, v94
	v_exp_f32_e32 v95, v95
	v_add_f32_e32 v94, 1.0, v94
	v_add_f32_e32 v95, 1.0, v95
	v_rcp_f32_e32 v94, v94
	v_rcp_f32_e32 v95, v95
	s_nop 0
	v_mul_f32_e32 v92, v92, v94
	v_mul_f32_e32 v93, v93, v95
	v_mul_f32_e32 v94, 0xbfb8aa3b, v82
	v_mul_f32_e32 v95, 0xbfb8aa3b, v83
	v_exp_f32_e32 v94, v94
	v_exp_f32_e32 v95, v95
	v_mul_f32_e32 v92, v96, v92
	v_mul_f32_e32 v93, v97, v93
	v_add_f32_e32 v94, 1.0, v94
	v_add_f32_e32 v95, 1.0, v95
	v_rcp_f32_e32 v94, v94
	v_rcp_f32_e32 v95, v95
	s_nop 0
	v_mul_f32_e32 v82, v82, v94
	v_mul_f32_e32 v83, v83, v95
	s_nop 0
	v_mul_f32_e32 v86, v86, v82
	v_mul_f32_e32 v87, v87, v83
	v_mul_f32_e32 v82, v84, v98
	v_mul_f32_e32 v83, v85, v98
	v_or_b32_e32 v94, 32, v130
	v_mul_f32_e32 v84, 0xbfb8aa3b, v82
	v_mul_f32_e32 v85, 0xbfb8aa3b, v83
	v_exp_f32_e32 v84, v84
	v_exp_f32_e32 v85, v85
	v_add_f32_e32 v84, 1.0, v84
	v_add_f32_e32 v85, 1.0, v85
	v_rcp_f32_e32 v84, v84
	v_rcp_f32_e32 v85, v85
	s_nop 0
	v_mul_f32_e32 v82, v82, v84
	v_mul_f32_e32 v83, v83, v85
	s_nop 0
	v_mul_f32_e32 v88, v88, v82
	v_mul_f32_e32 v89, v89, v83
	v_cvt_pk_bf16_f32 v84, v86, v87
	v_mad_i64_i32 v[86:87], s[18:19], v94, s67, v[114:115]
	v_cvt_pk_bf16_f32 v82, v90, v91
	v_cvt_pk_bf16_f32 v83, v92, v93
	v_cvt_pk_bf16_f32 v85, v88, v89
	v_lshl_add_u64 v[86:87], v[86:87], 0, v[116:117]
	global_store_dwordx4 v[86:87], v[82:85], off sc0 sc1
	s_nop 1
	v_mov_b32_e32 v82, v99
	v_mul_f32_e32 v74, v74, v82
	v_mul_f32_e32 v75, v75, v82
	s_nop 0
	v_mul_f32_e32 v83, 0xbfb8aa3b, v74
	v_exp_f32_e32 v83, v83
	s_nop 0
	v_add_f32_e32 v83, 1.0, v83
	v_rcp_f32_e32 v84, v83
	v_mul_f32_e32 v78, v78, v82
	v_mul_f32_e32 v79, v79, v82
	v_mul_f32_e32 v83, 0xbfb8aa3b, v75
	v_exp_f32_e32 v83, v83
	s_nop 0
	v_add_f32_e32 v83, 1.0, v83
	v_rcp_f32_e32 v85, v83
	v_mul_f32_e32 v76, v76, v82
	v_mul_f32_e32 v77, v77, v82
	v_mul_f32_e32 v66, v66, v82
	v_mul_f32_e32 v67, v67, v82
	v_mul_f32_e32 v70, v70, v82
	v_mul_f32_e32 v71, v71, v82
	v_mul_f32_e32 v74, v74, v84
	v_mul_f32_e32 v75, v75, v85
	v_mul_f32_e32 v80, v80, v82
	v_mul_f32_e32 v81, v81, v82
	v_mul_f32_e32 v74, v78, v74
	v_mul_f32_e32 v75, v79, v75
	v_mul_f32_e32 v78, 0xbfb8aa3b, v76
	v_mul_f32_e32 v79, 0xbfb8aa3b, v77
	v_exp_f32_e32 v78, v78
	v_exp_f32_e32 v79, v79
	v_mul_f32_e32 v72, v72, v82
	v_mul_f32_e32 v73, v73, v82
	v_add_f32_e32 v78, 1.0, v78
	v_add_f32_e32 v79, 1.0, v79
	v_rcp_f32_e32 v78, v78
	v_rcp_f32_e32 v79, v79
	s_nop 0
	v_mul_f32_e32 v76, v76, v78
	v_mul_f32_e32 v77, v77, v79
	v_mul_f32_e32 v78, 0xbfb8aa3b, v66
	v_mul_f32_e32 v79, 0xbfb8aa3b, v67
	v_exp_f32_e32 v78, v78
	v_exp_f32_e32 v79, v79
	v_mul_f32_e32 v76, v80, v76
	v_mul_f32_e32 v77, v81, v77
	v_add_f32_e32 v78, 1.0, v78
	v_add_f32_e32 v79, 1.0, v79
	v_rcp_f32_e32 v78, v78
	v_rcp_f32_e32 v79, v79
	s_nop 0
	v_mul_f32_e32 v66, v66, v78
	v_mul_f32_e32 v67, v67, v79
	s_nop 0
	v_mul_f32_e32 v70, v70, v66
	v_mul_f32_e32 v71, v71, v67
	v_mul_f32_e32 v66, v68, v82
	v_mul_f32_e32 v67, v69, v82
	v_or_b32_e32 v78, 48, v130
	v_mul_f32_e32 v68, 0xbfb8aa3b, v66
	v_mul_f32_e32 v69, 0xbfb8aa3b, v67
	v_exp_f32_e32 v68, v68
	v_exp_f32_e32 v69, v69
	v_add_f32_e32 v68, 1.0, v68
	v_add_f32_e32 v69, 1.0, v69
	v_rcp_f32_e32 v68, v68
	v_rcp_f32_e32 v69, v69
	s_nop 0
	v_mul_f32_e32 v66, v66, v68
	v_mul_f32_e32 v67, v67, v69
	s_nop 0
	v_mul_f32_e32 v72, v72, v66
	v_mul_f32_e32 v73, v73, v67
	v_cvt_pk_bf16_f32 v68, v70, v71
	v_mad_i64_i32 v[70:71], s[18:19], v78, s67, v[114:115]
	v_cvt_pk_bf16_f32 v66, v74, v75
	v_cvt_pk_bf16_f32 v67, v76, v77
	v_cvt_pk_bf16_f32 v69, v72, v73
	v_lshl_add_u64 v[70:71], v[70:71], 0, v[116:117]
	global_store_dwordx4 v[70:71], v[66:69], off sc0 sc1
	ds_read2_b32 v[66:67], v131 offset0:128 offset1:144
	v_add_u32_e32 v70, 0x80, v130
	s_waitcnt lgkmcnt(0)
	v_mul_f32_e32 v58, v58, v66
	v_mul_f32_e32 v59, v59, v66
	s_nop 0
	v_mul_f32_e32 v68, 0xbfb8aa3b, v58
	v_mul_f32_e32 v69, 0xbfb8aa3b, v59
	v_exp_f32_e32 v68, v68
	v_exp_f32_e32 v69, v69
	v_mul_f32_e32 v62, v62, v66
	v_mul_f32_e32 v63, v63, v66
	v_mul_f32_e32 v60, v60, v66
	v_mul_f32_e32 v61, v61, v66
	v_add_f32_e32 v68, 1.0, v68
	v_add_f32_e32 v69, 1.0, v69
	v_rcp_f32_e32 v68, v68
	v_rcp_f32_e32 v69, v69
	v_mul_f32_e32 v50, v50, v66
	v_mul_f32_e32 v51, v51, v66
	v_mul_f32_e32 v54, v54, v66
	v_mul_f32_e32 v55, v55, v66
	v_mul_f32_e32 v64, v64, v66
	v_mul_f32_e32 v65, v65, v66
	v_mul_f32_e32 v58, v58, v68
	v_mul_f32_e32 v59, v59, v69
	v_mul_f32_e32 v56, v56, v66
	v_mul_f32_e32 v57, v57, v66
	v_mul_f32_e32 v58, v62, v58
	v_mul_f32_e32 v59, v63, v59
	v_mul_f32_e32 v62, 0xbfb8aa3b, v60
	v_mul_f32_e32 v63, 0xbfb8aa3b, v61
	v_exp_f32_e32 v62, v62
	v_exp_f32_e32 v63, v63
	v_add_f32_e32 v62, 1.0, v62
	v_add_f32_e32 v63, 1.0, v63
	v_rcp_f32_e32 v62, v62
	v_rcp_f32_e32 v63, v63
	s_nop 0
	v_mul_f32_e32 v60, v60, v62
	v_mul_f32_e32 v61, v61, v63
	v_mul_f32_e32 v62, 0xbfb8aa3b, v50
	v_mul_f32_e32 v63, 0xbfb8aa3b, v51
	v_exp_f32_e32 v62, v62
	v_exp_f32_e32 v63, v63
	v_mul_f32_e32 v60, v64, v60
	v_mul_f32_e32 v61, v65, v61
	v_add_f32_e32 v62, 1.0, v62
	v_add_f32_e32 v63, 1.0, v63
	v_rcp_f32_e32 v62, v62
	v_rcp_f32_e32 v63, v63
	s_nop 0
	v_mul_f32_e32 v50, v50, v62
	v_mul_f32_e32 v51, v51, v63
	s_nop 0
	v_mul_f32_e32 v54, v54, v50
	v_mul_f32_e32 v55, v55, v51
	v_mul_f32_e32 v50, v52, v66
	v_mul_f32_e32 v51, v53, v66
	s_nop 0
	v_mul_f32_e32 v52, 0xbfb8aa3b, v50
	v_mul_f32_e32 v53, 0xbfb8aa3b, v51
	v_exp_f32_e32 v52, v52
	v_exp_f32_e32 v53, v53
	v_add_f32_e32 v52, 1.0, v52
	v_add_f32_e32 v53, 1.0, v53
	v_rcp_f32_e32 v52, v52
	v_rcp_f32_e32 v53, v53
	s_nop 0
	v_mul_f32_e32 v50, v50, v52
	v_mul_f32_e32 v51, v51, v53
	s_nop 0
	v_mul_f32_e32 v56, v56, v50
	v_mul_f32_e32 v57, v57, v51
	v_cvt_pk_bf16_f32 v52, v54, v55
	v_mad_i64_i32 v[54:55], s[18:19], v70, s67, v[114:115]
	v_cvt_pk_bf16_f32 v50, v58, v59
	v_cvt_pk_bf16_f32 v51, v60, v61
	v_cvt_pk_bf16_f32 v53, v56, v57
	v_lshl_add_u64 v[54:55], v[54:55], 0, v[116:117]
	global_store_dwordx4 v[54:55], v[50:53], off sc0 sc1
	s_nop 1
	v_mov_b32_e32 v50, v67
	v_mul_f32_e32 v42, v42, v50
	v_mul_f32_e32 v43, v43, v50
	s_nop 0
	v_mul_f32_e32 v51, 0xbfb8aa3b, v42
	v_exp_f32_e32 v51, v51
	s_nop 0
	v_add_f32_e32 v51, 1.0, v51
	v_rcp_f32_e32 v52, v51
	v_mul_f32_e32 v46, v46, v50
	v_mul_f32_e32 v47, v47, v50
	v_mul_f32_e32 v51, 0xbfb8aa3b, v43
	v_exp_f32_e32 v51, v51
	s_nop 0
	v_add_f32_e32 v51, 1.0, v51
	v_rcp_f32_e32 v53, v51
	v_mul_f32_e32 v44, v44, v50
	v_mul_f32_e32 v45, v45, v50
	v_mul_f32_e32 v34, v34, v50
	v_mul_f32_e32 v35, v35, v50
	v_mul_f32_e32 v38, v38, v50
	v_mul_f32_e32 v39, v39, v50
	v_mul_f32_e32 v42, v42, v52
	v_mul_f32_e32 v43, v43, v53
	v_mul_f32_e32 v48, v48, v50
	v_mul_f32_e32 v49, v49, v50
	v_mul_f32_e32 v42, v46, v42
	v_mul_f32_e32 v43, v47, v43
	v_mul_f32_e32 v46, 0xbfb8aa3b, v44
	v_mul_f32_e32 v47, 0xbfb8aa3b, v45
	v_exp_f32_e32 v46, v46
	v_exp_f32_e32 v47, v47
	v_mul_f32_e32 v40, v40, v50
	v_mul_f32_e32 v41, v41, v50
	v_add_f32_e32 v46, 1.0, v46
	v_add_f32_e32 v47, 1.0, v47
	v_rcp_f32_e32 v46, v46
	v_rcp_f32_e32 v47, v47
	s_nop 0
	v_mul_f32_e32 v44, v44, v46
	v_mul_f32_e32 v45, v45, v47
	v_mul_f32_e32 v46, 0xbfb8aa3b, v34
	v_mul_f32_e32 v47, 0xbfb8aa3b, v35
	v_exp_f32_e32 v46, v46
	v_exp_f32_e32 v47, v47
	v_mul_f32_e32 v44, v48, v44
	v_mul_f32_e32 v45, v49, v45
	v_add_f32_e32 v46, 1.0, v46
	v_add_f32_e32 v47, 1.0, v47
	v_rcp_f32_e32 v46, v46
	v_rcp_f32_e32 v47, v47
	s_nop 0
	v_mul_f32_e32 v34, v34, v46
	v_mul_f32_e32 v35, v35, v47
	s_nop 0
	v_mul_f32_e32 v38, v38, v34
	v_mul_f32_e32 v39, v39, v35
	v_mul_f32_e32 v34, v36, v50
	v_mul_f32_e32 v35, v37, v50
	v_add_u32_e32 v46, 0x90, v130
	v_mul_f32_e32 v36, 0xbfb8aa3b, v34
	v_mul_f32_e32 v37, 0xbfb8aa3b, v35
	v_exp_f32_e32 v36, v36
	v_exp_f32_e32 v37, v37
	v_add_f32_e32 v36, 1.0, v36
	v_add_f32_e32 v37, 1.0, v37
	v_rcp_f32_e32 v36, v36
	v_rcp_f32_e32 v37, v37
	s_nop 0
	v_mul_f32_e32 v34, v34, v36
	v_mul_f32_e32 v35, v35, v37
	s_nop 0
	v_mul_f32_e32 v40, v40, v34
	v_mul_f32_e32 v41, v41, v35
	v_cvt_pk_bf16_f32 v36, v38, v39
	v_mad_i64_i32 v[38:39], s[18:19], v46, s67, v[114:115]
	v_cvt_pk_bf16_f32 v34, v42, v43
	v_cvt_pk_bf16_f32 v35, v44, v45
	v_cvt_pk_bf16_f32 v37, v40, v41
	v_lshl_add_u64 v[38:39], v[38:39], 0, v[116:117]
	global_store_dwordx4 v[38:39], v[34:37], off sc0 sc1
	ds_read2_b32 v[34:35], v131 offset0:160 offset1:176
	s_waitcnt lgkmcnt(0)
	v_mul_f32_e32 v26, v26, v34
	v_mul_f32_e32 v27, v27, v34
	s_nop 0
	v_mul_f32_e32 v36, 0xbfb8aa3b, v26
	v_mul_f32_e32 v37, 0xbfb8aa3b, v27
	v_exp_f32_e32 v36, v36
	v_exp_f32_e32 v37, v37
	v_mul_f32_e32 v30, v30, v34
	v_mul_f32_e32 v31, v31, v34
	v_mul_f32_e32 v28, v28, v34
	v_mul_f32_e32 v29, v29, v34
	v_add_f32_e32 v36, 1.0, v36
	v_add_f32_e32 v37, 1.0, v37
	v_rcp_f32_e32 v36, v36
	v_rcp_f32_e32 v37, v37
	v_mul_f32_e32 v18, v18, v34
	v_mul_f32_e32 v19, v19, v34
	v_mul_f32_e32 v22, v22, v34
	v_mul_f32_e32 v23, v23, v34
	v_mul_f32_e32 v32, v32, v34
	v_mul_f32_e32 v33, v33, v34
	v_mul_f32_e32 v26, v26, v36
	v_mul_f32_e32 v27, v27, v37
	v_mul_f32_e32 v24, v24, v34
	v_mul_f32_e32 v25, v25, v34
	v_mul_f32_e32 v26, v30, v26
	v_mul_f32_e32 v27, v31, v27
	v_mul_f32_e32 v30, 0xbfb8aa3b, v28
	v_mul_f32_e32 v31, 0xbfb8aa3b, v29
	v_exp_f32_e32 v30, v30
	v_exp_f32_e32 v31, v31
	v_add_f32_e32 v30, 1.0, v30
	v_add_f32_e32 v31, 1.0, v31
	v_rcp_f32_e32 v30, v30
	v_rcp_f32_e32 v31, v31
	s_nop 0
	v_mul_f32_e32 v28, v28, v30
	v_mul_f32_e32 v29, v29, v31
	v_mul_f32_e32 v30, 0xbfb8aa3b, v18
	v_mul_f32_e32 v31, 0xbfb8aa3b, v19
	v_exp_f32_e32 v30, v30
	v_exp_f32_e32 v31, v31
	v_mul_f32_e32 v28, v32, v28
	v_mul_f32_e32 v29, v33, v29
	v_add_f32_e32 v30, 1.0, v30
	v_add_f32_e32 v31, 1.0, v31
	v_rcp_f32_e32 v30, v30
	v_rcp_f32_e32 v31, v31
	s_nop 0
	v_mul_f32_e32 v18, v18, v30
	v_mul_f32_e32 v19, v19, v31
	s_nop 0
	v_mul_f32_e32 v22, v22, v18
	v_mul_f32_e32 v23, v23, v19
	v_mul_f32_e32 v18, v20, v34
	v_mul_f32_e32 v19, v21, v34
	v_add_u32_e32 v30, 0xa0, v130
	v_mul_f32_e32 v20, 0xbfb8aa3b, v18
	v_mul_f32_e32 v21, 0xbfb8aa3b, v19
	v_exp_f32_e32 v20, v20
	v_exp_f32_e32 v21, v21
	v_add_f32_e32 v20, 1.0, v20
	v_add_f32_e32 v21, 1.0, v21
	v_rcp_f32_e32 v20, v20
	v_rcp_f32_e32 v21, v21
	s_nop 0
	v_mul_f32_e32 v18, v18, v20
	v_mul_f32_e32 v19, v19, v21
	s_nop 0
	v_mul_f32_e32 v24, v24, v18
	v_mul_f32_e32 v25, v25, v19
	v_cvt_pk_bf16_f32 v20, v22, v23
	v_mad_i64_i32 v[22:23], s[18:19], v30, s67, v[114:115]
	v_cvt_pk_bf16_f32 v18, v26, v27
	v_cvt_pk_bf16_f32 v19, v28, v29
	v_cvt_pk_bf16_f32 v21, v24, v25
	v_lshl_add_u64 v[22:23], v[22:23], 0, v[116:117]
	global_store_dwordx4 v[22:23], v[18:21], off sc0 sc1
	s_nop 1
	v_mov_b32_e32 v18, v35
	v_mul_f32_e32 v10, v10, v18
	v_mul_f32_e32 v11, v11, v18
	s_nop 0
	v_mul_f32_e32 v19, 0xbfb8aa3b, v10
	v_exp_f32_e32 v19, v19
	s_nop 0
	v_add_f32_e32 v19, 1.0, v19
	v_rcp_f32_e32 v20, v19
	v_mul_f32_e32 v14, v14, v18
	v_mul_f32_e32 v15, v15, v18
	v_mul_f32_e32 v19, 0xbfb8aa3b, v11
	v_exp_f32_e32 v19, v19
	s_nop 0
	v_add_f32_e32 v19, 1.0, v19
	v_rcp_f32_e32 v21, v19
	v_mul_f32_e32 v12, v12, v18
	v_mul_f32_e32 v13, v13, v18
	v_mul_f32_e32 v2, v2, v18
	v_mul_f32_e32 v3, v3, v18
	v_mul_f32_e32 v6, v6, v18
	v_mul_f32_e32 v7, v7, v18
	v_mul_f32_e32 v10, v10, v20
	v_mul_f32_e32 v11, v11, v21
	v_mul_f32_e32 v16, v16, v18
	v_mul_f32_e32 v17, v17, v18
	v_mul_f32_e32 v10, v14, v10
	v_mul_f32_e32 v11, v15, v11
	v_mul_f32_e32 v14, 0xbfb8aa3b, v12
	v_mul_f32_e32 v15, 0xbfb8aa3b, v13
	v_exp_f32_e32 v14, v14
	v_exp_f32_e32 v15, v15
	v_mul_f32_e32 v8, v8, v18
	v_mul_f32_e32 v9, v9, v18
	v_add_f32_e32 v14, 1.0, v14
	v_add_f32_e32 v15, 1.0, v15
	v_rcp_f32_e32 v14, v14
	v_rcp_f32_e32 v15, v15
	s_nop 0
	v_mul_f32_e32 v12, v12, v14
	v_mul_f32_e32 v13, v13, v15
	v_mul_f32_e32 v14, 0xbfb8aa3b, v2
	v_mul_f32_e32 v15, 0xbfb8aa3b, v3
	v_exp_f32_e32 v14, v14
	v_exp_f32_e32 v15, v15
	v_mul_f32_e32 v12, v16, v12
	v_mul_f32_e32 v13, v17, v13
	v_add_f32_e32 v14, 1.0, v14
	v_add_f32_e32 v15, 1.0, v15
	v_rcp_f32_e32 v14, v14
	v_rcp_f32_e32 v15, v15
	s_nop 0
	v_mul_f32_e32 v2, v2, v14
	v_mul_f32_e32 v3, v3, v15
	s_nop 0
	v_mul_f32_e32 v6, v6, v2
	v_mul_f32_e32 v7, v7, v3
	v_mul_f32_e32 v2, v4, v18
	v_mul_f32_e32 v3, v5, v18
	v_add_u32_e32 v14, 0xb0, v130
	v_mul_f32_e32 v4, 0xbfb8aa3b, v2
	v_mul_f32_e32 v5, 0xbfb8aa3b, v3
	v_exp_f32_e32 v4, v4
	v_exp_f32_e32 v5, v5
	v_add_f32_e32 v4, 1.0, v4
	v_add_f32_e32 v5, 1.0, v5
	v_rcp_f32_e32 v4, v4
	v_rcp_f32_e32 v5, v5
	s_nop 0
	v_mul_f32_e32 v2, v2, v4
	v_mul_f32_e32 v3, v3, v5
	s_nop 0
	v_mul_f32_e32 v8, v8, v2
	v_mul_f32_e32 v9, v9, v3
	v_cvt_pk_bf16_f32 v4, v6, v7
	v_mad_i64_i32 v[6:7], s[18:19], v14, s67, v[114:115]
	v_cvt_pk_bf16_f32 v2, v10, v11
	v_cvt_pk_bf16_f32 v3, v12, v13
	v_cvt_pk_bf16_f32 v5, v8, v9
	v_lshl_add_u64 v[6:7], v[6:7], 0, v[116:117]
	global_store_dwordx4 v[6:7], v[2:5], off sc0 sc1
	s_cbranch_vccnz .LBB0_266
	s_andn2_b64 vcc, exec, s[0:1]
	s_cbranch_vccnz .LBB0_265
	s_barrier
	s_branch .LBB0_265

.LBB0_1942:
	v_lshl_add_u32 v131, s82, 10, v220
	ds_read2_b32 v[134:135], v131 offset1:16
	v_lshl_or_b32 v132, s83, 7, v219
	v_lshl_add_u32 v130, s40, 8, v1
	v_ashrrev_i32_e32 v133, 31, v132
	s_andn2_b64 vcc, exec, s[36:37]
	s_waitcnt lgkmcnt(0)
	v_mul_f32_e32 v122, v122, v134
	v_mul_f32_e32 v123, v123, v134
	v_mul_f32_e32 v126, v126, v134
	v_mul_f32_e32 v127, v127, v134
	v_mul_f32_e32 v136, 0xbfb8aa3b, v122
	v_mul_f32_e32 v137, 0xbfb8aa3b, v123
	v_exp_f32_e32 v136, v136
	v_exp_f32_e32 v137, v137
	v_mul_f32_e32 v124, v124, v134
	v_mul_f32_e32 v125, v125, v134
	v_mul_f32_e32 v114, v114, v134
	v_mul_f32_e32 v115, v115, v134
	v_add_f32_e32 v136, 1.0, v136
	v_add_f32_e32 v137, 1.0, v137
	v_rcp_f32_e32 v136, v136
	v_rcp_f32_e32 v137, v137
	v_mul_f32_e32 v118, v118, v134
	v_mul_f32_e32 v119, v119, v134
	v_mul_f32_e32 v116, v116, v134
	v_mul_f32_e32 v117, v117, v134
	v_mul_f32_e32 v120, v120, v134
	v_mul_f32_e32 v121, v121, v134
	v_mul_f32_e32 v122, v122, v136
	v_mul_f32_e32 v123, v123, v137
	v_mul_f32_e32 v128, v128, v134
	v_mul_f32_e32 v129, v129, v134
	v_mul_f32_e32 v122, v126, v122
	v_mul_f32_e32 v123, v127, v123
	v_mul_f32_e32 v126, 0xbfb8aa3b, v124
	v_mul_f32_e32 v127, 0xbfb8aa3b, v125
	v_exp_f32_e32 v126, v126
	v_exp_f32_e32 v127, v127
	v_add_f32_e32 v126, 1.0, v126
	v_add_f32_e32 v127, 1.0, v127
	v_rcp_f32_e32 v126, v126
	v_rcp_f32_e32 v127, v127
	s_nop 0
	v_mul_f32_e32 v124, v124, v126
	v_mul_f32_e32 v125, v125, v127
	v_mul_f32_e32 v126, 0xbfb8aa3b, v114
	v_mul_f32_e32 v127, 0xbfb8aa3b, v115
	v_exp_f32_e32 v126, v126
	v_exp_f32_e32 v127, v127
	v_mul_f32_e32 v124, v128, v124
	v_mul_f32_e32 v125, v129, v125
	v_add_f32_e32 v126, 1.0, v126
	v_add_f32_e32 v127, 1.0, v127
	v_rcp_f32_e32 v126, v126
	v_rcp_f32_e32 v127, v127
	s_nop 0
	v_mul_f32_e32 v114, v114, v126
	v_mul_f32_e32 v115, v115, v127
	s_nop 0
	v_mul_f32_e32 v114, v118, v114
	v_mul_f32_e32 v115, v119, v115
	v_mul_f32_e32 v118, 0xbfb8aa3b, v116
	v_mul_f32_e32 v119, 0xbfb8aa3b, v117
	v_exp_f32_e32 v118, v118
	v_exp_f32_e32 v119, v119
	v_add_f32_e32 v118, 1.0, v118
	v_add_f32_e32 v119, 1.0, v119
	v_rcp_f32_e32 v118, v118
	v_rcp_f32_e32 v119, v119
	s_nop 0
	v_mul_f32_e32 v116, v116, v118
	v_mul_f32_e32 v117, v117, v119
	s_nop 0
	v_mul_f32_e32 v116, v120, v116
	v_mul_f32_e32 v117, v121, v117
	v_cvt_pk_bf16_f32 v120, v114, v115
	v_mov_b64_e32 v[114:115], s[54:55]
	v_cvt_pk_bf16_f32 v118, v122, v123
	v_cvt_pk_bf16_f32 v121, v116, v117
	v_mad_i64_i32 v[122:123], s[14:15], v130, s73, v[114:115]
	v_lshlrev_b64 v[116:117], 1, v[132:133]
	v_cvt_pk_bf16_f32 v119, v124, v125
	v_lshl_add_u64 v[122:123], v[122:123], 0, v[116:117]
	global_store_dwordx4 v[122:123], v[118:121], off
	s_nop 1
	v_mov_b32_e32 v118, v135
	v_mul_f32_e32 v106, v106, v118
	v_mul_f32_e32 v107, v107, v118
	s_nop 0
	v_mul_f32_e32 v119, 0xbfb8aa3b, v106
	v_exp_f32_e32 v119, v119
	s_nop 0
	v_add_f32_e32 v119, 1.0, v119
	v_rcp_f32_e32 v120, v119
	v_mul_f32_e32 v110, v110, v118
	v_mul_f32_e32 v111, v111, v118
	v_mul_f32_e32 v119, 0xbfb8aa3b, v107
	v_exp_f32_e32 v119, v119
	s_nop 0
	v_add_f32_e32 v119, 1.0, v119
	v_rcp_f32_e32 v121, v119
	v_mul_f32_e32 v108, v108, v118
	v_mul_f32_e32 v109, v109, v118
	v_mul_f32_e32 v98, v98, v118
	v_mul_f32_e32 v99, v99, v118
	v_mul_f32_e32 v102, v102, v118
	v_mul_f32_e32 v103, v103, v118
	v_mul_f32_e32 v106, v106, v120
	v_mul_f32_e32 v107, v107, v121
	v_mul_f32_e32 v112, v112, v118
	v_mul_f32_e32 v113, v113, v118
	v_mul_f32_e32 v106, v110, v106
	v_mul_f32_e32 v107, v111, v107
	v_mul_f32_e32 v110, 0xbfb8aa3b, v108
	v_mul_f32_e32 v111, 0xbfb8aa3b, v109
	v_exp_f32_e32 v110, v110
	v_exp_f32_e32 v111, v111
	v_mul_f32_e32 v104, v104, v118
	v_mul_f32_e32 v105, v105, v118
	v_add_f32_e32 v110, 1.0, v110
	v_add_f32_e32 v111, 1.0, v111
	v_rcp_f32_e32 v110, v110
	v_rcp_f32_e32 v111, v111
	s_nop 0
	v_mul_f32_e32 v108, v108, v110
	v_mul_f32_e32 v109, v109, v111
	v_mul_f32_e32 v110, 0xbfb8aa3b, v98
	v_mul_f32_e32 v111, 0xbfb8aa3b, v99
	v_exp_f32_e32 v110, v110
	v_exp_f32_e32 v111, v111
	v_mul_f32_e32 v108, v112, v108
	v_mul_f32_e32 v109, v113, v109
	v_add_f32_e32 v110, 1.0, v110
	v_add_f32_e32 v111, 1.0, v111
	v_rcp_f32_e32 v110, v110
	v_rcp_f32_e32 v111, v111
	s_nop 0
	v_mul_f32_e32 v98, v98, v110
	v_mul_f32_e32 v99, v99, v111
	s_nop 0
	v_mul_f32_e32 v102, v102, v98
	v_mul_f32_e32 v103, v103, v99
	v_mul_f32_e32 v98, v100, v118
	v_mul_f32_e32 v99, v101, v118
	v_or_b32_e32 v110, 16, v130
	v_mul_f32_e32 v100, 0xbfb8aa3b, v98
	v_mul_f32_e32 v101, 0xbfb8aa3b, v99
	v_exp_f32_e32 v100, v100
	v_exp_f32_e32 v101, v101
	v_add_f32_e32 v100, 1.0, v100
	v_add_f32_e32 v101, 1.0, v101
	v_rcp_f32_e32 v100, v100
	v_rcp_f32_e32 v101, v101
	s_nop 0
	v_mul_f32_e32 v98, v98, v100
	v_mul_f32_e32 v99, v99, v101
	s_nop 0
	v_mul_f32_e32 v104, v104, v98
	v_mul_f32_e32 v105, v105, v99
	v_cvt_pk_bf16_f32 v100, v102, v103
	v_mad_i64_i32 v[102:103], s[14:15], v110, s73, v[114:115]
	v_cvt_pk_bf16_f32 v98, v106, v107
	v_cvt_pk_bf16_f32 v99, v108, v109
	v_cvt_pk_bf16_f32 v101, v104, v105
	v_lshl_add_u64 v[102:103], v[102:103], 0, v[116:117]
	global_store_dwordx4 v[102:103], v[98:101], off
	ds_read2_b32 v[98:99], v131 offset0:32 offset1:48
	s_waitcnt lgkmcnt(0)
	v_mul_f32_e32 v90, v90, v98
	v_mul_f32_e32 v91, v91, v98
	s_nop 0
	v_mul_f32_e32 v100, 0xbfb8aa3b, v90
	v_mul_f32_e32 v101, 0xbfb8aa3b, v91
	v_exp_f32_e32 v100, v100
	v_exp_f32_e32 v101, v101
	v_mul_f32_e32 v94, v94, v98
	v_mul_f32_e32 v95, v95, v98
	v_mul_f32_e32 v92, v92, v98
	v_mul_f32_e32 v93, v93, v98
	v_add_f32_e32 v100, 1.0, v100
	v_add_f32_e32 v101, 1.0, v101
	v_rcp_f32_e32 v100, v100
	v_rcp_f32_e32 v101, v101
	v_mul_f32_e32 v82, v82, v98
	v_mul_f32_e32 v83, v83, v98
	v_mul_f32_e32 v86, v86, v98
	v_mul_f32_e32 v87, v87, v98
	v_mul_f32_e32 v96, v96, v98
	v_mul_f32_e32 v97, v97, v98
	v_mul_f32_e32 v90, v90, v100
	v_mul_f32_e32 v91, v91, v101
	v_mul_f32_e32 v88, v88, v98
	v_mul_f32_e32 v89, v89, v98
	v_mul_f32_e32 v90, v94, v90
	v_mul_f32_e32 v91, v95, v91
	v_mul_f32_e32 v94, 0xbfb8aa3b, v92
	v_mul_f32_e32 v95, 0xbfb8aa3b, v93
	v_exp_f32_e32 v94, v94
	v_exp_f32_e32 v95, v95
	v_add_f32_e32 v94, 1.0, v94
	v_add_f32_e32 v95, 1.0, v95
	v_rcp_f32_e32 v94, v94
	v_rcp_f32_e32 v95, v95
	s_nop 0
	v_mul_f32_e32 v92, v92, v94
	v_mul_f32_e32 v93, v93, v95
	v_mul_f32_e32 v94, 0xbfb8aa3b, v82
	v_mul_f32_e32 v95, 0xbfb8aa3b, v83
	v_exp_f32_e32 v94, v94
	v_exp_f32_e32 v95, v95
	v_mul_f32_e32 v92, v96, v92
	v_mul_f32_e32 v93, v97, v93
	v_add_f32_e32 v94, 1.0, v94
	v_add_f32_e32 v95, 1.0, v95
	v_rcp_f32_e32 v94, v94
	v_rcp_f32_e32 v95, v95
	s_nop 0
	v_mul_f32_e32 v82, v82, v94
	v_mul_f32_e32 v83, v83, v95
	s_nop 0
	v_mul_f32_e32 v86, v86, v82
	v_mul_f32_e32 v87, v87, v83
	v_mul_f32_e32 v82, v84, v98
	v_mul_f32_e32 v83, v85, v98
	v_or_b32_e32 v94, 32, v130
	v_mul_f32_e32 v84, 0xbfb8aa3b, v82
	v_mul_f32_e32 v85, 0xbfb8aa3b, v83
	v_exp_f32_e32 v84, v84
	v_exp_f32_e32 v85, v85
	v_add_f32_e32 v84, 1.0, v84
	v_add_f32_e32 v85, 1.0, v85
	v_rcp_f32_e32 v84, v84
	v_rcp_f32_e32 v85, v85
	s_nop 0
	v_mul_f32_e32 v82, v82, v84
	v_mul_f32_e32 v83, v83, v85
	s_nop 0
	v_mul_f32_e32 v88, v88, v82
	v_mul_f32_e32 v89, v89, v83
	v_cvt_pk_bf16_f32 v84, v86, v87
	v_mad_i64_i32 v[86:87], s[14:15], v94, s73, v[114:115]
	v_cvt_pk_bf16_f32 v82, v90, v91
	v_cvt_pk_bf16_f32 v83, v92, v93
	v_cvt_pk_bf16_f32 v85, v88, v89
	v_lshl_add_u64 v[86:87], v[86:87], 0, v[116:117]
	global_store_dwordx4 v[86:87], v[82:85], off
	s_nop 1
	v_mov_b32_e32 v82, v99
	v_mul_f32_e32 v74, v74, v82
	v_mul_f32_e32 v75, v75, v82
	s_nop 0
	v_mul_f32_e32 v83, 0xbfb8aa3b, v74
	v_exp_f32_e32 v83, v83
	s_nop 0
	v_add_f32_e32 v83, 1.0, v83
	v_rcp_f32_e32 v84, v83
	v_mul_f32_e32 v78, v78, v82
	v_mul_f32_e32 v79, v79, v82
	v_mul_f32_e32 v83, 0xbfb8aa3b, v75
	v_exp_f32_e32 v83, v83
	s_nop 0
	v_add_f32_e32 v83, 1.0, v83
	v_rcp_f32_e32 v85, v83
	v_mul_f32_e32 v76, v76, v82
	v_mul_f32_e32 v77, v77, v82
	v_mul_f32_e32 v66, v66, v82
	v_mul_f32_e32 v67, v67, v82
	v_mul_f32_e32 v70, v70, v82
	v_mul_f32_e32 v71, v71, v82
	v_mul_f32_e32 v74, v74, v84
	v_mul_f32_e32 v75, v75, v85
	v_mul_f32_e32 v80, v80, v82
	v_mul_f32_e32 v81, v81, v82
	v_mul_f32_e32 v74, v78, v74
	v_mul_f32_e32 v75, v79, v75
	v_mul_f32_e32 v78, 0xbfb8aa3b, v76
	v_mul_f32_e32 v79, 0xbfb8aa3b, v77
	v_exp_f32_e32 v78, v78
	v_exp_f32_e32 v79, v79
	v_mul_f32_e32 v72, v72, v82
	v_mul_f32_e32 v73, v73, v82
	v_add_f32_e32 v78, 1.0, v78
	v_add_f32_e32 v79, 1.0, v79
	v_rcp_f32_e32 v78, v78
	v_rcp_f32_e32 v79, v79
	s_nop 0
	v_mul_f32_e32 v76, v76, v78
	v_mul_f32_e32 v77, v77, v79
	v_mul_f32_e32 v78, 0xbfb8aa3b, v66
	v_mul_f32_e32 v79, 0xbfb8aa3b, v67
	v_exp_f32_e32 v78, v78
	v_exp_f32_e32 v79, v79
	v_mul_f32_e32 v76, v80, v76
	v_mul_f32_e32 v77, v81, v77
	v_add_f32_e32 v78, 1.0, v78
	v_add_f32_e32 v79, 1.0, v79
	v_rcp_f32_e32 v78, v78
	v_rcp_f32_e32 v79, v79
	s_nop 0
	v_mul_f32_e32 v66, v66, v78
	v_mul_f32_e32 v67, v67, v79
	s_nop 0
	v_mul_f32_e32 v70, v70, v66
	v_mul_f32_e32 v71, v71, v67
	v_mul_f32_e32 v66, v68, v82
	v_mul_f32_e32 v67, v69, v82
	v_or_b32_e32 v78, 48, v130
	v_mul_f32_e32 v68, 0xbfb8aa3b, v66
	v_mul_f32_e32 v69, 0xbfb8aa3b, v67
	v_exp_f32_e32 v68, v68
	v_exp_f32_e32 v69, v69
	v_add_f32_e32 v68, 1.0, v68
	v_add_f32_e32 v69, 1.0, v69
	v_rcp_f32_e32 v68, v68
	v_rcp_f32_e32 v69, v69
	s_nop 0
	v_mul_f32_e32 v66, v66, v68
	v_mul_f32_e32 v67, v67, v69
	s_nop 0
	v_mul_f32_e32 v72, v72, v66
	v_mul_f32_e32 v73, v73, v67
	v_cvt_pk_bf16_f32 v68, v70, v71
	v_mad_i64_i32 v[70:71], s[14:15], v78, s73, v[114:115]
	v_cvt_pk_bf16_f32 v66, v74, v75
	v_cvt_pk_bf16_f32 v67, v76, v77
	v_cvt_pk_bf16_f32 v69, v72, v73
	v_lshl_add_u64 v[70:71], v[70:71], 0, v[116:117]
	global_store_dwordx4 v[70:71], v[66:69], off
	ds_read2_b32 v[66:67], v131 offset0:128 offset1:144
	v_add_u32_e32 v70, 0x80, v130
	s_waitcnt lgkmcnt(0)
	v_mul_f32_e32 v58, v58, v66
	v_mul_f32_e32 v59, v59, v66
	s_nop 0
	v_mul_f32_e32 v68, 0xbfb8aa3b, v58
	v_mul_f32_e32 v69, 0xbfb8aa3b, v59
	v_exp_f32_e32 v68, v68
	v_exp_f32_e32 v69, v69
	v_mul_f32_e32 v62, v62, v66
	v_mul_f32_e32 v63, v63, v66
	v_mul_f32_e32 v60, v60, v66
	v_mul_f32_e32 v61, v61, v66
	v_add_f32_e32 v68, 1.0, v68
	v_add_f32_e32 v69, 1.0, v69
	v_rcp_f32_e32 v68, v68
	v_rcp_f32_e32 v69, v69
	v_mul_f32_e32 v50, v50, v66
	v_mul_f32_e32 v51, v51, v66
	v_mul_f32_e32 v54, v54, v66
	v_mul_f32_e32 v55, v55, v66
	v_mul_f32_e32 v64, v64, v66
	v_mul_f32_e32 v65, v65, v66
	v_mul_f32_e32 v58, v58, v68
	v_mul_f32_e32 v59, v59, v69
	v_mul_f32_e32 v56, v56, v66
	v_mul_f32_e32 v57, v57, v66
	v_mul_f32_e32 v58, v62, v58
	v_mul_f32_e32 v59, v63, v59
	v_mul_f32_e32 v62, 0xbfb8aa3b, v60
	v_mul_f32_e32 v63, 0xbfb8aa3b, v61
	v_exp_f32_e32 v62, v62
	v_exp_f32_e32 v63, v63
	v_add_f32_e32 v62, 1.0, v62
	v_add_f32_e32 v63, 1.0, v63
	v_rcp_f32_e32 v62, v62
	v_rcp_f32_e32 v63, v63
	s_nop 0
	v_mul_f32_e32 v60, v60, v62
	v_mul_f32_e32 v61, v61, v63
	v_mul_f32_e32 v62, 0xbfb8aa3b, v50
	v_mul_f32_e32 v63, 0xbfb8aa3b, v51
	v_exp_f32_e32 v62, v62
	v_exp_f32_e32 v63, v63
	v_mul_f32_e32 v60, v64, v60
	v_mul_f32_e32 v61, v65, v61
	v_add_f32_e32 v62, 1.0, v62
	v_add_f32_e32 v63, 1.0, v63
	v_rcp_f32_e32 v62, v62
	v_rcp_f32_e32 v63, v63
	s_nop 0
	v_mul_f32_e32 v50, v50, v62
	v_mul_f32_e32 v51, v51, v63
	s_nop 0
	v_mul_f32_e32 v54, v54, v50
	v_mul_f32_e32 v55, v55, v51
	v_mul_f32_e32 v50, v52, v66
	v_mul_f32_e32 v51, v53, v66
	s_nop 0
	v_mul_f32_e32 v52, 0xbfb8aa3b, v50
	v_mul_f32_e32 v53, 0xbfb8aa3b, v51
	v_exp_f32_e32 v52, v52
	v_exp_f32_e32 v53, v53
	v_add_f32_e32 v52, 1.0, v52
	v_add_f32_e32 v53, 1.0, v53
	v_rcp_f32_e32 v52, v52
	v_rcp_f32_e32 v53, v53
	s_nop 0
	v_mul_f32_e32 v50, v50, v52
	v_mul_f32_e32 v51, v51, v53
	s_nop 0
	v_mul_f32_e32 v56, v56, v50
	v_mul_f32_e32 v57, v57, v51
	v_cvt_pk_bf16_f32 v52, v54, v55
	v_mad_i64_i32 v[54:55], s[14:15], v70, s73, v[114:115]
	v_cvt_pk_bf16_f32 v50, v58, v59
	v_cvt_pk_bf16_f32 v51, v60, v61
	v_cvt_pk_bf16_f32 v53, v56, v57
	v_lshl_add_u64 v[54:55], v[54:55], 0, v[116:117]
	global_store_dwordx4 v[54:55], v[50:53], off
	s_nop 1
	v_mov_b32_e32 v50, v67
	v_mul_f32_e32 v42, v42, v50
	v_mul_f32_e32 v43, v43, v50
	s_nop 0
	v_mul_f32_e32 v51, 0xbfb8aa3b, v42
	v_exp_f32_e32 v51, v51
	s_nop 0
	v_add_f32_e32 v51, 1.0, v51
	v_rcp_f32_e32 v52, v51
	v_mul_f32_e32 v46, v46, v50
	v_mul_f32_e32 v47, v47, v50
	v_mul_f32_e32 v51, 0xbfb8aa3b, v43
	v_exp_f32_e32 v51, v51
	s_nop 0
	v_add_f32_e32 v51, 1.0, v51
	v_rcp_f32_e32 v53, v51
	v_mul_f32_e32 v44, v44, v50
	v_mul_f32_e32 v45, v45, v50
	v_mul_f32_e32 v34, v34, v50
	v_mul_f32_e32 v35, v35, v50
	v_mul_f32_e32 v38, v38, v50
	v_mul_f32_e32 v39, v39, v50
	v_mul_f32_e32 v42, v42, v52
	v_mul_f32_e32 v43, v43, v53
	v_mul_f32_e32 v48, v48, v50
	v_mul_f32_e32 v49, v49, v50
	v_mul_f32_e32 v42, v46, v42
	v_mul_f32_e32 v43, v47, v43
	v_mul_f32_e32 v46, 0xbfb8aa3b, v44
	v_mul_f32_e32 v47, 0xbfb8aa3b, v45
	v_exp_f32_e32 v46, v46
	v_exp_f32_e32 v47, v47
	v_mul_f32_e32 v40, v40, v50
	v_mul_f32_e32 v41, v41, v50
	v_add_f32_e32 v46, 1.0, v46
	v_add_f32_e32 v47, 1.0, v47
	v_rcp_f32_e32 v46, v46
	v_rcp_f32_e32 v47, v47
	s_nop 0
	v_mul_f32_e32 v44, v44, v46
	v_mul_f32_e32 v45, v45, v47
	v_mul_f32_e32 v46, 0xbfb8aa3b, v34
	v_mul_f32_e32 v47, 0xbfb8aa3b, v35
	v_exp_f32_e32 v46, v46
	v_exp_f32_e32 v47, v47
	v_mul_f32_e32 v44, v48, v44
	v_mul_f32_e32 v45, v49, v45
	v_add_f32_e32 v46, 1.0, v46
	v_add_f32_e32 v47, 1.0, v47
	v_rcp_f32_e32 v46, v46
	v_rcp_f32_e32 v47, v47
	s_nop 0
	v_mul_f32_e32 v34, v34, v46
	v_mul_f32_e32 v35, v35, v47
	s_nop 0
	v_mul_f32_e32 v38, v38, v34
	v_mul_f32_e32 v39, v39, v35
	v_mul_f32_e32 v34, v36, v50
	v_mul_f32_e32 v35, v37, v50
	v_add_u32_e32 v46, 0x90, v130
	v_mul_f32_e32 v36, 0xbfb8aa3b, v34
	v_mul_f32_e32 v37, 0xbfb8aa3b, v35
	v_exp_f32_e32 v36, v36
	v_exp_f32_e32 v37, v37
	v_add_f32_e32 v36, 1.0, v36
	v_add_f32_e32 v37, 1.0, v37
	v_rcp_f32_e32 v36, v36
	v_rcp_f32_e32 v37, v37
	s_nop 0
	v_mul_f32_e32 v34, v34, v36
	v_mul_f32_e32 v35, v35, v37
	s_nop 0
	v_mul_f32_e32 v40, v40, v34
	v_mul_f32_e32 v41, v41, v35
	v_cvt_pk_bf16_f32 v36, v38, v39
	v_mad_i64_i32 v[38:39], s[14:15], v46, s73, v[114:115]
	v_cvt_pk_bf16_f32 v34, v42, v43
	v_cvt_pk_bf16_f32 v35, v44, v45
	v_cvt_pk_bf16_f32 v37, v40, v41
	v_lshl_add_u64 v[38:39], v[38:39], 0, v[116:117]
	global_store_dwordx4 v[38:39], v[34:37], off
	ds_read2_b32 v[34:35], v131 offset0:160 offset1:176
	s_waitcnt lgkmcnt(0)
	v_mul_f32_e32 v26, v26, v34
	v_mul_f32_e32 v27, v27, v34
	s_nop 0
	v_mul_f32_e32 v36, 0xbfb8aa3b, v26
	v_mul_f32_e32 v37, 0xbfb8aa3b, v27
	v_exp_f32_e32 v36, v36
	v_exp_f32_e32 v37, v37
	v_mul_f32_e32 v30, v30, v34
	v_mul_f32_e32 v31, v31, v34
	v_mul_f32_e32 v28, v28, v34
	v_mul_f32_e32 v29, v29, v34
	v_add_f32_e32 v36, 1.0, v36
	v_add_f32_e32 v37, 1.0, v37
	v_rcp_f32_e32 v36, v36
	v_rcp_f32_e32 v37, v37
	v_mul_f32_e32 v18, v18, v34
	v_mul_f32_e32 v19, v19, v34
	v_mul_f32_e32 v22, v22, v34
	v_mul_f32_e32 v23, v23, v34
	v_mul_f32_e32 v32, v32, v34
	v_mul_f32_e32 v33, v33, v34
	v_mul_f32_e32 v26, v26, v36
	v_mul_f32_e32 v27, v27, v37
	v_mul_f32_e32 v24, v24, v34
	v_mul_f32_e32 v25, v25, v34
	v_mul_f32_e32 v26, v30, v26
	v_mul_f32_e32 v27, v31, v27
	v_mul_f32_e32 v30, 0xbfb8aa3b, v28
	v_mul_f32_e32 v31, 0xbfb8aa3b, v29
	v_exp_f32_e32 v30, v30
	v_exp_f32_e32 v31, v31
	v_add_f32_e32 v30, 1.0, v30
	v_add_f32_e32 v31, 1.0, v31
	v_rcp_f32_e32 v30, v30
	v_rcp_f32_e32 v31, v31
	s_nop 0
	v_mul_f32_e32 v28, v28, v30
	v_mul_f32_e32 v29, v29, v31
	v_mul_f32_e32 v30, 0xbfb8aa3b, v18
	v_mul_f32_e32 v31, 0xbfb8aa3b, v19
	v_exp_f32_e32 v30, v30
	v_exp_f32_e32 v31, v31
	v_mul_f32_e32 v28, v32, v28
	v_mul_f32_e32 v29, v33, v29
	v_add_f32_e32 v30, 1.0, v30
	v_add_f32_e32 v31, 1.0, v31
	v_rcp_f32_e32 v30, v30
	v_rcp_f32_e32 v31, v31
	s_nop 0
	v_mul_f32_e32 v18, v18, v30
	v_mul_f32_e32 v19, v19, v31
	s_nop 0
	v_mul_f32_e32 v22, v22, v18
	v_mul_f32_e32 v23, v23, v19
	v_mul_f32_e32 v18, v20, v34
	v_mul_f32_e32 v19, v21, v34
	v_add_u32_e32 v30, 0xa0, v130
	v_mul_f32_e32 v20, 0xbfb8aa3b, v18
	v_mul_f32_e32 v21, 0xbfb8aa3b, v19
	v_exp_f32_e32 v20, v20
	v_exp_f32_e32 v21, v21
	v_add_f32_e32 v20, 1.0, v20
	v_add_f32_e32 v21, 1.0, v21
	v_rcp_f32_e32 v20, v20
	v_rcp_f32_e32 v21, v21
	s_nop 0
	v_mul_f32_e32 v18, v18, v20
	v_mul_f32_e32 v19, v19, v21
	s_nop 0
	v_mul_f32_e32 v24, v24, v18
	v_mul_f32_e32 v25, v25, v19
	v_cvt_pk_bf16_f32 v20, v22, v23
	v_mad_i64_i32 v[22:23], s[14:15], v30, s73, v[114:115]
	v_cvt_pk_bf16_f32 v18, v26, v27
	v_cvt_pk_bf16_f32 v19, v28, v29
	v_cvt_pk_bf16_f32 v21, v24, v25
	v_lshl_add_u64 v[22:23], v[22:23], 0, v[116:117]
	global_store_dwordx4 v[22:23], v[18:21], off
	s_nop 1
	v_mov_b32_e32 v18, v35
	v_mul_f32_e32 v10, v10, v18
	v_mul_f32_e32 v11, v11, v18
	s_nop 0
	v_mul_f32_e32 v19, 0xbfb8aa3b, v10
	v_exp_f32_e32 v19, v19
	s_nop 0
	v_add_f32_e32 v19, 1.0, v19
	v_rcp_f32_e32 v20, v19
	v_mul_f32_e32 v14, v14, v18
	v_mul_f32_e32 v15, v15, v18
	v_mul_f32_e32 v19, 0xbfb8aa3b, v11
	v_exp_f32_e32 v19, v19
	s_nop 0
	v_add_f32_e32 v19, 1.0, v19
	v_rcp_f32_e32 v21, v19
	v_mul_f32_e32 v12, v12, v18
	v_mul_f32_e32 v13, v13, v18
	v_mul_f32_e32 v2, v2, v18
	v_mul_f32_e32 v3, v3, v18
	v_mul_f32_e32 v6, v6, v18
	v_mul_f32_e32 v7, v7, v18
	v_mul_f32_e32 v10, v10, v20
	v_mul_f32_e32 v11, v11, v21
	v_mul_f32_e32 v16, v16, v18
	v_mul_f32_e32 v17, v17, v18
	v_mul_f32_e32 v10, v14, v10
	v_mul_f32_e32 v11, v15, v11
	v_mul_f32_e32 v14, 0xbfb8aa3b, v12
	v_mul_f32_e32 v15, 0xbfb8aa3b, v13
	v_exp_f32_e32 v14, v14
	v_exp_f32_e32 v15, v15
	v_mul_f32_e32 v8, v8, v18
	v_mul_f32_e32 v9, v9, v18
	v_add_f32_e32 v14, 1.0, v14
	v_add_f32_e32 v15, 1.0, v15
	v_rcp_f32_e32 v14, v14
	v_rcp_f32_e32 v15, v15
	s_nop 0
	v_mul_f32_e32 v12, v12, v14
	v_mul_f32_e32 v13, v13, v15
	v_mul_f32_e32 v14, 0xbfb8aa3b, v2
	v_mul_f32_e32 v15, 0xbfb8aa3b, v3
	v_exp_f32_e32 v14, v14
	v_exp_f32_e32 v15, v15
	v_mul_f32_e32 v12, v16, v12
	v_mul_f32_e32 v13, v17, v13
	v_add_f32_e32 v14, 1.0, v14
	v_add_f32_e32 v15, 1.0, v15
	v_rcp_f32_e32 v14, v14
	v_rcp_f32_e32 v15, v15
	s_nop 0
	v_mul_f32_e32 v2, v2, v14
	v_mul_f32_e32 v3, v3, v15
	s_nop 0
	v_mul_f32_e32 v6, v6, v2
	v_mul_f32_e32 v7, v7, v3
	v_mul_f32_e32 v2, v4, v18
	v_mul_f32_e32 v3, v5, v18
	v_add_u32_e32 v14, 0xb0, v130
	v_mul_f32_e32 v4, 0xbfb8aa3b, v2
	v_mul_f32_e32 v5, 0xbfb8aa3b, v3
	v_exp_f32_e32 v4, v4
	v_exp_f32_e32 v5, v5
	v_add_f32_e32 v4, 1.0, v4
	v_add_f32_e32 v5, 1.0, v5
	v_rcp_f32_e32 v4, v4
	v_rcp_f32_e32 v5, v5
	s_nop 0
	v_mul_f32_e32 v2, v2, v4
	v_mul_f32_e32 v3, v3, v5
	s_nop 0
	v_mul_f32_e32 v8, v8, v2
	v_mul_f32_e32 v9, v9, v3
	v_cvt_pk_bf16_f32 v4, v6, v7
	v_mad_i64_i32 v[6:7], s[14:15], v14, s73, v[114:115]
	v_cvt_pk_bf16_f32 v2, v10, v11
	v_cvt_pk_bf16_f32 v3, v12, v13
	v_cvt_pk_bf16_f32 v5, v8, v9
	v_lshl_add_u64 v[6:7], v[6:7], 0, v[116:117]
	s_mov_b64 s[14:15], -1
	global_store_dwordx4 v[6:7], v[2:5], off
	s_cbranch_vccnz .LBB0_1923
	s_andn2_b64 vcc, exec, s[0:1]
	s_cbranch_vccnz .LBB0_1922
	s_barrier
	s_branch .LBB0_1922
